# in-projection GEMM (P2, P7) epilogue stores made write-through as well
# baseline (speedup 1.0000x reference)
; __device__ __forceinline__ unsigned cvt_pk_bf16(float lo, float hi) { unsigned r; asm volatile("v_cvt_pk_bf16_f32 %0, %1, %2" : "=v"(r) : "v"(lo), "v"(hi)); return r; }
;     __device__ __forceinline__ void operator()(const f32x4 (&acc)[2][2][4][2], const Unit& u, int wr, int wc, int fr, int fq) const {
;         const int row0 = u.pm * BM + wr * 64 + fr; const int col0 = u.pn * BM + wc * 32 + 8 * fq;
; #pragma unroll
;         for (int ai = 0; ai < 2; ++ai)
; #pragma unroll
;             for (int m = 0; m < 4; ++m) { bf16_t* rowp = O + (size_t)(row0 + ai * HALF + m * 16) * ldc + col0;
; #pragma unroll
;                 for (int bj = 0; bj < 2; ++bj) { const f32x4 v0 = acc[ai][bj][m][0], v1 = acc[ai][bj][m][1];
;                     u32x4 w; w.x = cvt_pk_bf16(v0[0], v0[1]); w.y = cvt_pk_bf16(v0[2], v0[3]); w.z = cvt_pk_bf16(v1[0], v1[1]); w.w = cvt_pk_bf16(v1[2], v1[3]);
;                     *(u32x4*)(rowp + bj * HALF) = w; } }
.LBB0_207:
	v_lshl_add_u32 v146, s51, 8, v150
	v_lshl_add_u32 v156, s22, 8, v148
	v_ashrrev_i32_e32 v147, 31, v146
	v_mov_b64_e32 v[144:145], s[76:77]
	v_mad_i64_i32 v[154:155], s[24:25], v156, s50, v[144:145]
	v_lshlrev_b64 v[146:147], 1, v[146:147]
	v_lshl_add_u64 v[154:155], v[154:155], 0, v[146:147]
	v_cvt_pk_bf16_f32 v124, v124, v125
	v_cvt_pk_bf16_f32 v125, v126, v127
	v_cvt_pk_bf16_f32 v126, v120, v121
	v_cvt_pk_bf16_f32 v127, v122, v123
	global_store_dwordx4 v[154:155], v[124:127], off sc1
	v_cvt_pk_bf16_f32 v112, v112, v113
	v_cvt_pk_bf16_f32 v113, v114, v115
	v_cvt_pk_bf16_f32 v114, v104, v105
	v_or_b32_e32 v104, 16, v156
	v_mad_i64_i32 v[104:105], s[24:25], v104, s50, v[144:145]
	v_cvt_pk_bf16_f32 v115, v106, v107
	global_store_dwordx4 v[154:155], v[112:115], off offset:256 sc1
	s_andn2_b64 vcc, exec, s[2:3]
	s_mov_b64 s[2:3], -1
	v_lshl_add_u64 v[112:113], v[104:105], 0, v[146:147]
	v_cvt_pk_bf16_f32 v104, v116, v117
	v_cvt_pk_bf16_f32 v105, v118, v119
	v_cvt_pk_bf16_f32 v106, v108, v109
	v_cvt_pk_bf16_f32 v107, v110, v111
	global_store_dwordx4 v[112:113], v[104:107], off sc1
	v_cvt_pk_bf16_f32 v96, v96, v97
	v_cvt_pk_bf16_f32 v97, v98, v99
	v_cvt_pk_bf16_f32 v98, v88, v89
	v_or_b32_e32 v88, 32, v156
	v_mad_i64_i32 v[88:89], s[24:25], v88, s50, v[144:145]
	v_cvt_pk_bf16_f32 v99, v90, v91
	global_store_dwordx4 v[112:113], v[96:99], off offset:256 sc1
	s_nop 1
	v_lshl_add_u64 v[96:97], v[88:89], 0, v[146:147]
	v_cvt_pk_bf16_f32 v88, v100, v101
	v_cvt_pk_bf16_f32 v89, v102, v103
	v_cvt_pk_bf16_f32 v90, v92, v93
	v_cvt_pk_bf16_f32 v91, v94, v95
	global_store_dwordx4 v[96:97], v[88:91], off sc1
	v_cvt_pk_bf16_f32 v80, v80, v81
	v_cvt_pk_bf16_f32 v81, v82, v83
	v_cvt_pk_bf16_f32 v82, v72, v73
	v_or_b32_e32 v72, 48, v156
	v_mad_i64_i32 v[72:73], s[24:25], v72, s50, v[144:145]
	v_cvt_pk_bf16_f32 v83, v74, v75
	global_store_dwordx4 v[96:97], v[80:83], off offset:256 sc1
	s_nop 1
	v_lshl_add_u64 v[80:81], v[72:73], 0, v[146:147]
	v_cvt_pk_bf16_f32 v72, v84, v85
	v_cvt_pk_bf16_f32 v73, v86, v87
	v_cvt_pk_bf16_f32 v74, v76, v77
	v_cvt_pk_bf16_f32 v75, v78, v79
	global_store_dwordx4 v[80:81], v[72:75], off sc1
	v_cvt_pk_bf16_f32 v68, v68, v69
	v_cvt_pk_bf16_f32 v69, v70, v71
	v_cvt_pk_bf16_f32 v70, v64, v65
	v_add_u32_e32 v64, 0x80, v156
	v_mad_i64_i32 v[64:65], s[24:25], v64, s50, v[144:145]
	v_lshl_add_u64 v[64:65], v[64:65], 0, v[146:147]
	v_cvt_pk_bf16_f32 v71, v66, v67
	global_store_dwordx4 v[80:81], v[68:71], off offset:256 sc1
	v_cvt_pk_bf16_f32 v60, v60, v61
	v_cvt_pk_bf16_f32 v61, v62, v63
	v_cvt_pk_bf16_f32 v62, v56, v57
	v_cvt_pk_bf16_f32 v63, v58, v59
	global_store_dwordx4 v[64:65], v[60:63], off sc1
	v_cvt_pk_bf16_f32 v48, v48, v49
	v_cvt_pk_bf16_f32 v49, v50, v51
	v_cvt_pk_bf16_f32 v50, v40, v41
	v_add_u32_e32 v40, 0x90, v156
	v_mad_i64_i32 v[40:41], s[24:25], v40, s50, v[144:145]
	v_cvt_pk_bf16_f32 v51, v42, v43
	global_store_dwordx4 v[64:65], v[48:51], off offset:256 sc1
	s_nop 1
	v_lshl_add_u64 v[48:49], v[40:41], 0, v[146:147]
	v_cvt_pk_bf16_f32 v40, v52, v53
	v_cvt_pk_bf16_f32 v41, v54, v55
	v_cvt_pk_bf16_f32 v42, v44, v45
	v_cvt_pk_bf16_f32 v43, v46, v47
	global_store_dwordx4 v[48:49], v[40:43], off sc1
	v_cvt_pk_bf16_f32 v32, v32, v33
	v_cvt_pk_bf16_f32 v33, v34, v35
	v_cvt_pk_bf16_f32 v34, v24, v25
	v_add_u32_e32 v24, 0xa0, v156
	v_mad_i64_i32 v[24:25], s[24:25], v24, s50, v[144:145]
	v_cvt_pk_bf16_f32 v35, v26, v27
	global_store_dwordx4 v[48:49], v[32:35], off offset:256 sc1
	s_nop 1
	v_lshl_add_u64 v[32:33], v[24:25], 0, v[146:147]
	v_cvt_pk_bf16_f32 v24, v36, v37
	v_cvt_pk_bf16_f32 v25, v38, v39
	v_cvt_pk_bf16_f32 v26, v28, v29
	v_cvt_pk_bf16_f32 v27, v30, v31
	global_store_dwordx4 v[32:33], v[24:27], off sc1
	v_cvt_pk_bf16_f32 v16, v16, v17
	v_cvt_pk_bf16_f32 v17, v18, v19
	v_cvt_pk_bf16_f32 v18, v8, v9
	v_add_u32_e32 v8, 0xb0, v156
	v_mad_i64_i32 v[8:9], s[24:25], v8, s50, v[144:145]
	v_cvt_pk_bf16_f32 v19, v10, v11
	global_store_dwordx4 v[32:33], v[16:19], off offset:256 sc1
	s_nop 1
	v_lshl_add_u64 v[16:17], v[8:9], 0, v[146:147]
	v_cvt_pk_bf16_f32 v8, v20, v21
	v_cvt_pk_bf16_f32 v9, v22, v23
	v_cvt_pk_bf16_f32 v10, v12, v13
	v_cvt_pk_bf16_f32 v11, v14, v15
	global_store_dwordx4 v[16:17], v[8:11], off sc1
	v_cvt_pk_bf16_f32 v4, v4, v5
	v_cvt_pk_bf16_f32 v5, v6, v7
	v_cvt_pk_bf16_f32 v6, v0, v1
	v_cvt_pk_bf16_f32 v7, v2, v3
	global_store_dwordx4 v[16:17], v[4:7], off offset:256 sc1
	s_cbranch_vccnz .LBB0_200
	s_andn2_b64 vcc, exec, s[8:9]
	s_cbranch_vccnz .LBB0_199
	s_barrier
	s_branch .LBB0_199

; __device__ __forceinline__ unsigned cvt_pk_bf16(float lo, float hi) { unsigned r; asm volatile("v_cvt_pk_bf16_f32 %0, %1, %2" : "=v"(r) : "v"(lo), "v"(hi)); return r; }
;     __device__ __forceinline__ void operator()(const f32x4 (&acc)[2][2][4][2], const Unit& u, int wr, int wc, int fr, int fq) const {
;         const int row0 = u.pm * BM + wr * 64 + fr; const int col0 = u.pn * BM + wc * 32 + 8 * fq;
; #pragma unroll
;         for (int ai = 0; ai < 2; ++ai)
; #pragma unroll
;             for (int m = 0; m < 4; ++m) { bf16_t* rowp = O + (size_t)(row0 + ai * HALF + m * 16) * ldc + col0;
; #pragma unroll
;                 for (int bj = 0; bj < 2; ++bj) { const f32x4 v0 = acc[ai][bj][m][0], v1 = acc[ai][bj][m][1];
;                     u32x4 w; w.x = cvt_pk_bf16(v0[0], v0[1]); w.y = cvt_pk_bf16(v0[2], v0[3]); w.z = cvt_pk_bf16(v1[0], v1[1]); w.w = cvt_pk_bf16(v1[2], v1[3]);
;                     *(u32x4*)(rowp + bj * HALF) = w; } }
.LBB0_231:
	v_lshl_add_u32 v152, s24, 8, v146
	v_lshl_add_u32 v144, s50, 8, v148
	v_ashrrev_i32_e32 v153, 31, v152
	v_ashrrev_i32_e32 v145, 31, v144
	v_lshlrev_b64 v[154:155], 16, v[152:153]
	v_lshl_add_u64 v[154:155], s[80:81], 0, v[154:155]
	v_lshlrev_b64 v[156:157], 1, v[144:145]
	v_lshl_add_u64 v[144:145], v[154:155], 0, v[156:157]
	v_cvt_pk_bf16_f32 v124, v124, v125
	v_cvt_pk_bf16_f32 v125, v126, v127
	v_cvt_pk_bf16_f32 v126, v120, v121
	v_cvt_pk_bf16_f32 v127, v122, v123
	global_store_dwordx4 v[144:145], v[124:127], off sc1
	v_cvt_pk_bf16_f32 v112, v112, v113
	v_cvt_pk_bf16_f32 v113, v114, v115
	v_cvt_pk_bf16_f32 v114, v104, v105
	v_or_b32_e32 v104, 16, v152
	v_ashrrev_i32_e32 v105, 31, v104
	v_lshlrev_b64 v[104:105], 16, v[104:105]
	v_lshl_add_u64 v[104:105], s[80:81], 0, v[104:105]
	v_cvt_pk_bf16_f32 v115, v106, v107
	global_store_dwordx4 v[144:145], v[112:115], off offset:256 sc1
	s_mov_b32 s17, 0x800000
	s_mov_b64 s[26:27], 0x800000
	v_lshl_add_u64 v[112:113], v[104:105], 0, v[156:157]
	v_cvt_pk_bf16_f32 v104, v116, v117
	v_cvt_pk_bf16_f32 v105, v118, v119
	v_cvt_pk_bf16_f32 v106, v108, v109
	v_cvt_pk_bf16_f32 v107, v110, v111
	global_store_dwordx4 v[112:113], v[104:107], off sc1
	v_cvt_pk_bf16_f32 v96, v96, v97
	v_cvt_pk_bf16_f32 v97, v98, v99
	v_cvt_pk_bf16_f32 v98, v88, v89
	v_or_b32_e32 v88, 32, v152
	v_ashrrev_i32_e32 v89, 31, v88
	v_lshlrev_b64 v[88:89], 16, v[88:89]
	v_lshl_add_u64 v[88:89], s[80:81], 0, v[88:89]
	v_cvt_pk_bf16_f32 v99, v90, v91
	global_store_dwordx4 v[112:113], v[96:99], off offset:256 sc1
	s_nop 1
	v_lshl_add_u64 v[96:97], v[88:89], 0, v[156:157]
	v_cvt_pk_bf16_f32 v88, v100, v101
	v_cvt_pk_bf16_f32 v89, v102, v103
	v_cvt_pk_bf16_f32 v90, v92, v93
	v_cvt_pk_bf16_f32 v91, v94, v95
	global_store_dwordx4 v[96:97], v[88:91], off sc1
	v_cvt_pk_bf16_f32 v80, v80, v81
	v_cvt_pk_bf16_f32 v81, v82, v83
	v_cvt_pk_bf16_f32 v82, v72, v73
	v_or_b32_e32 v72, 48, v152
	v_ashrrev_i32_e32 v73, 31, v72
	v_lshlrev_b64 v[72:73], 16, v[72:73]
	v_lshl_add_u64 v[72:73], s[80:81], 0, v[72:73]
	v_cvt_pk_bf16_f32 v83, v74, v75
	global_store_dwordx4 v[96:97], v[80:83], off offset:256 sc1
	s_nop 1
	v_lshl_add_u64 v[80:81], v[72:73], 0, v[156:157]
	v_cvt_pk_bf16_f32 v72, v84, v85
	v_cvt_pk_bf16_f32 v73, v86, v87
	v_cvt_pk_bf16_f32 v74, v76, v77
	v_cvt_pk_bf16_f32 v75, v78, v79
	global_store_dwordx4 v[80:81], v[72:75], off sc1
	v_cvt_pk_bf16_f32 v68, v68, v69
	v_cvt_pk_bf16_f32 v69, v70, v71
	v_cvt_pk_bf16_f32 v70, v64, v65
	v_cvt_pk_bf16_f32 v71, v66, v67
	global_store_dwordx4 v[80:81], v[68:71], off offset:256 sc1
	v_cvt_pk_bf16_f32 v60, v60, v61
	v_cvt_pk_bf16_f32 v61, v62, v63
	v_cvt_pk_bf16_f32 v62, v56, v57
	v_add_co_u32_e32 v56, vcc, s17, v144
	v_lshl_add_u64 v[64:65], v[144:145], 0, s[26:27]
	s_nop 0
	v_addc_co_u32_e32 v57, vcc, 0, v145, vcc
	s_mov_b32 s17, 0x900000
	v_cvt_pk_bf16_f32 v63, v58, v59
	global_store_dwordx4 v[56:57], v[60:63], off sc1
	v_cvt_pk_bf16_f32 v48, v48, v49
	v_cvt_pk_bf16_f32 v49, v50, v51
	v_cvt_pk_bf16_f32 v50, v40, v41
	v_cvt_pk_bf16_f32 v51, v42, v43
	global_store_dwordx4 v[64:65], v[48:51], off offset:256 sc1
	s_mov_b64 s[26:27], 0x900000
	v_cvt_pk_bf16_f32 v40, v52, v53
	v_cvt_pk_bf16_f32 v41, v54, v55
	v_cvt_pk_bf16_f32 v42, v44, v45
	v_add_co_u32_e32 v44, vcc, s17, v144
	v_lshl_add_u64 v[48:49], v[144:145], 0, s[26:27]
	s_nop 0
	v_addc_co_u32_e32 v45, vcc, 0, v145, vcc
	v_cvt_pk_bf16_f32 v43, v46, v47
	global_store_dwordx4 v[44:45], v[40:43], off sc1
	v_cvt_pk_bf16_f32 v32, v32, v33
	v_cvt_pk_bf16_f32 v33, v34, v35
	v_cvt_pk_bf16_f32 v34, v24, v25
	v_cvt_pk_bf16_f32 v35, v26, v27
	global_store_dwordx4 v[48:49], v[32:35], off offset:256 sc1
	v_cvt_pk_bf16_f32 v24, v36, v37
	v_cvt_pk_bf16_f32 v25, v38, v39
	v_cvt_pk_bf16_f32 v26, v28, v29
	v_add_co_u32_e32 v28, vcc, s47, v144
	s_nop 0
	v_lshl_add_u64 v[32:33], v[144:145], 0, s[12:13]
	v_addc_co_u32_e32 v29, vcc, 0, v145, vcc
	v_cvt_pk_bf16_f32 v27, v30, v31
	global_store_dwordx4 v[28:29], v[24:27], off sc1
	v_cvt_pk_bf16_f32 v16, v16, v17
	v_cvt_pk_bf16_f32 v17, v18, v19
	v_cvt_pk_bf16_f32 v18, v8, v9
	v_cvt_pk_bf16_f32 v19, v10, v11
	global_store_dwordx4 v[32:33], v[16:19], off offset:256 sc1
	v_cvt_pk_bf16_f32 v8, v20, v21
	v_cvt_pk_bf16_f32 v9, v22, v23
	v_cvt_pk_bf16_f32 v10, v12, v13
	v_add_co_u32_e32 v12, vcc, s49, v144
	s_nop 0
	v_lshl_add_u64 v[16:17], v[144:145], 0, s[14:15]
	v_addc_co_u32_e32 v13, vcc, 0, v145, vcc
	s_andn2_b64 vcc, exec, s[2:3]
	s_mov_b64 s[2:3], -1
	v_cvt_pk_bf16_f32 v11, v14, v15
	global_store_dwordx4 v[12:13], v[8:11], off sc1
	v_cvt_pk_bf16_f32 v4, v4, v5
	v_cvt_pk_bf16_f32 v5, v6, v7
	v_cvt_pk_bf16_f32 v6, v0, v1
	v_cvt_pk_bf16_f32 v7, v2, v3
	global_store_dwordx4 v[16:17], v[4:7], off offset:256 sc1
	s_cbranch_vccnz .LBB0_220
	s_andn2_b64 vcc, exec, s[4:5]
	s_cbranch_vccnz .LBB0_219
	s_barrier
	s_branch .LBB0_219

; __device__ __forceinline__ unsigned cvt_pk_bf16(float lo, float hi) { unsigned r; asm volatile("v_cvt_pk_bf16_f32 %0, %1, %2" : "=v"(r) : "v"(lo), "v"(hi)); return r; }
;     __device__ __forceinline__ void operator()(const f32x4 (&acc)[2][2][4][2], const Unit& u, int wr, int wc, int fr, int fq) const {
;         const int row0 = u.pm * BM + wr * 64 + fr; const int col0 = u.pn * BM + wc * 32 + 8 * fq;
;         const float* bp = bias + (size_t)((u.pm * BM) / 8192) * 4096 + col0;
;         f32x4 bv[2][2];
; #pragma unroll
;         for (int bj = 0; bj < 2; ++bj) { bv[bj][0] = *(const f32x4*)(bp + bj * HALF); bv[bj][1] = *(const f32x4*)(bp + bj * HALF + 4); }
; #pragma unroll
;         for (int ai = 0; ai < 2; ++ai)
; #pragma unroll
;             for (int m = 0; m < 4; ++m) { const int row = row0 + ai * HALF + m * 16; bf16_t* rowp = O + (size_t)row * ldc + col0;
;                 const float rs = 1.0f / sqrtf(rowss[row] * (1.f / 1024.f) + 1e-6f);
; #pragma unroll
;                 for (int bj = 0; bj < 2; ++bj) { const f32x4 v0 = acc[ai][bj][m][0] * rs + bv[bj][0], v1 = acc[ai][bj][m][1] * rs + bv[bj][1];
;                     u32x4 w; w.x = cvt_pk_bf16(v0[0], v0[1]); w.y = cvt_pk_bf16(v0[2], v0[3]); w.z = cvt_pk_bf16(v1[0], v1[1]); w.w = cvt_pk_bf16(v1[2], v1[3]);
;                     *(u32x4*)(rowp + bj * HALF) = w; } }
.LBB0_632:
	v_lshl_add_u32 v160, s2, 8, v168
	v_ashrrev_i32_e32 v161, 31, v160
	v_lshl_add_u64 v[164:165], v[160:161], 2, s[68:69]
	global_load_dword v161, v[164:165], off
	v_lshl_add_u32 v166, s3, 8, v170
	s_ashr_i32 s3, s2, 31
	s_lshr_b32 s3, s3, 27
	s_add_i32 s2, s2, s3
	s_ashr_i32 s2, s2, 5
	s_ashr_i32 s3, s2, 31
	s_lshl_b64 s[2:3], s[2:3], 14
	s_add_u32 s2, s90, s2
	v_ashrrev_i32_e32 v167, 31, v166
	s_addc_u32 s3, s91, s3
	v_lshl_add_u64 v[112:113], v[166:167], 2, s[2:3]
	global_load_dwordx4 v[124:127], v[112:113], off
	global_load_dwordx4 v[120:123], v[112:113], off offset:16
	global_load_dwordx4 v[116:119], v[112:113], off offset:512
	s_nop 0
	global_load_dwordx4 v[112:115], v[112:113], off offset:528
	v_mov_b64_e32 v[162:163], s[76:77]
	v_mad_i64_i32 v[176:177], s[2:3], v160, s47, v[162:163]
	v_or_b32_e32 v178, 16, v160
	v_lshlrev_b64 v[166:167], 1, v[166:167]
	v_lshl_add_u64 v[176:177], v[176:177], 0, v[166:167]
	s_waitcnt vmcnt(0)
	v_fmamk_f32 v161, v161, 0x3a800000, v174
	v_mul_f32_e32 v179, 0x4f800000, v161
	v_cmp_gt_f32_e32 vcc, s48, v161
	s_nop 1
	v_cndmask_b32_e32 v161, v161, v179, vcc
	v_sqrt_f32_e32 v180, v161
	v_ashrrev_i32_e32 v179, 31, v178
	v_add_u32_e32 v181, -1, v180
	v_add_u32_e32 v182, 1, v180
	v_fma_f32 v183, -v181, v180, v161
	v_fma_f32 v184, -v182, v180, v161
	v_cmp_ge_f32_e64 s[2:3], 0, v183
	s_nop 1
	v_cndmask_b32_e64 v180, v180, v181, s[2:3]
	v_cmp_lt_f32_e64 s[2:3], 0, v184
	s_nop 1
	v_cndmask_b32_e64 v180, v180, v182, s[2:3]
	v_mul_f32_e32 v181, 0x37800000, v180
	v_cndmask_b32_e32 v180, v180, v181, vcc
	v_cmp_class_f32_e32 vcc, v161, v175
	s_nop 1
	v_cndmask_b32_e32 v161, v180, v161, vcc
	v_div_scale_f32 v182, s[2:3], v161, v161, 1.0
	v_rcp_f32_e32 v183, v182
	v_lshl_add_u64 v[180:181], v[178:179], 2, s[68:69]
	v_div_scale_f32 v179, vcc, 1.0, v161, 1.0
	v_fma_f32 v184, -v182, v183, 1.0
	v_fmac_f32_e32 v183, v184, v183
	v_mul_f32_e32 v184, v179, v183
	v_fma_f32 v185, -v182, v184, v179
	v_fmac_f32_e32 v184, v185, v183
	v_fma_f32 v179, -v182, v184, v179
	v_div_fmas_f32 v179, v179, v183, v184
	v_div_fixup_f32 v182, v179, v161, 1.0
	v_pk_fma_f32 v[142:143], v[142:143], v[182:183], v[126:127] op_sel_hi:[1,0,1]
	v_pk_fma_f32 v[140:141], v[140:141], v[182:183], v[124:125] op_sel_hi:[1,0,1]
	v_pk_fma_f32 v[138:139], v[138:139], v[182:183], v[122:123] op_sel_hi:[1,0,1]
	v_pk_fma_f32 v[136:137], v[136:137], v[182:183], v[120:121] op_sel_hi:[1,0,1]
	v_pk_fma_f32 v[134:135], v[134:135], v[182:183], v[118:119] op_sel_hi:[1,0,1]
	v_pk_fma_f32 v[132:133], v[132:133], v[182:183], v[116:117] op_sel_hi:[1,0,1]
	v_pk_fma_f32 v[184:185], v[130:131], v[182:183], v[114:115] op_sel_hi:[1,0,1]
	v_pk_fma_f32 v[182:183], v[128:129], v[182:183], v[112:113] op_sel_hi:[1,0,1]
	v_cvt_pk_bf16_f32 v128, v140, v141
	v_cvt_pk_bf16_f32 v129, v142, v143
	v_cvt_pk_bf16_f32 v130, v136, v137
	v_cvt_pk_bf16_f32 v131, v138, v139
	global_store_dwordx4 v[176:177], v[128:131], off sc1
	s_nop 1
	v_cvt_pk_bf16_f32 v128, v132, v133
	v_cvt_pk_bf16_f32 v129, v134, v135
	v_cvt_pk_bf16_f32 v130, v182, v183
	v_cvt_pk_bf16_f32 v131, v184, v185
	global_store_dwordx4 v[176:177], v[128:131], off offset:256 sc1
	global_load_dword v129, v[180:181], off
	s_nop 0
	v_or_b32_e32 v128, 32, v160
	s_waitcnt vmcnt(0)
	v_fmamk_f32 v129, v129, 0x3a800000, v174
	v_mul_f32_e32 v130, 0x4f800000, v129
	v_cmp_gt_f32_e32 vcc, s48, v129
	s_nop 1
	v_cndmask_b32_e32 v132, v129, v130, vcc
	v_sqrt_f32_e32 v133, v132
	v_mad_i64_i32 v[130:131], s[2:3], v178, s47, v[162:163]
	v_ashrrev_i32_e32 v129, 31, v128
	v_add_u32_e32 v134, -1, v133
	v_add_u32_e32 v135, 1, v133
	v_fma_f32 v136, -v134, v133, v132
	v_fma_f32 v137, -v135, v133, v132
	v_cmp_ge_f32_e64 s[2:3], 0, v136
	v_lshl_add_u64 v[130:131], v[130:131], 0, v[166:167]
	s_nop 0
	v_cndmask_b32_e64 v133, v133, v134, s[2:3]
	v_cmp_lt_f32_e64 s[2:3], 0, v137
	s_nop 1
	v_cndmask_b32_e64 v133, v133, v135, s[2:3]
	v_mul_f32_e32 v134, 0x37800000, v133
	v_cndmask_b32_e32 v133, v133, v134, vcc
	v_cmp_class_f32_e32 vcc, v132, v175
	s_nop 1
	v_cndmask_b32_e32 v134, v133, v132, vcc
	v_div_scale_f32 v135, s[2:3], v134, v134, 1.0
	v_rcp_f32_e32 v136, v135
	v_lshl_add_u64 v[132:133], v[128:129], 2, s[68:69]
	v_div_scale_f32 v129, vcc, 1.0, v134, 1.0
	v_fma_f32 v137, -v135, v136, 1.0
	v_fmac_f32_e32 v136, v137, v136
	v_mul_f32_e32 v137, v129, v136
	v_fma_f32 v138, -v135, v137, v129
	v_fmac_f32_e32 v137, v138, v136
	v_fma_f32 v129, -v135, v137, v129
	v_div_fmas_f32 v129, v129, v136, v137
	v_div_fixup_f32 v134, v129, v134, 1.0
	v_pk_fma_f32 v[110:111], v[110:111], v[134:135], v[126:127] op_sel_hi:[1,0,1]
	v_pk_fma_f32 v[108:109], v[108:109], v[134:135], v[124:125] op_sel_hi:[1,0,1]
	v_pk_fma_f32 v[106:107], v[106:107], v[134:135], v[122:123] op_sel_hi:[1,0,1]
	v_pk_fma_f32 v[104:105], v[104:105], v[134:135], v[120:121] op_sel_hi:[1,0,1]
	v_pk_fma_f32 v[102:103], v[102:103], v[134:135], v[118:119] op_sel_hi:[1,0,1]
	v_pk_fma_f32 v[100:101], v[100:101], v[134:135], v[116:117] op_sel_hi:[1,0,1]
	v_pk_fma_f32 v[136:137], v[98:99], v[134:135], v[114:115] op_sel_hi:[1,0,1]
	v_pk_fma_f32 v[134:135], v[96:97], v[134:135], v[112:113] op_sel_hi:[1,0,1]
	v_cvt_pk_bf16_f32 v96, v108, v109
	v_cvt_pk_bf16_f32 v97, v110, v111
	v_cvt_pk_bf16_f32 v98, v104, v105
	v_cvt_pk_bf16_f32 v99, v106, v107
	global_store_dwordx4 v[130:131], v[96:99], off sc1
	s_nop 1
	v_cvt_pk_bf16_f32 v96, v100, v101
	v_cvt_pk_bf16_f32 v97, v102, v103
	v_cvt_pk_bf16_f32 v98, v134, v135
	v_cvt_pk_bf16_f32 v99, v136, v137
	global_store_dwordx4 v[130:131], v[96:99], off offset:256 sc1
	global_load_dword v97, v[132:133], off
	s_nop 0
	v_or_b32_e32 v96, 48, v160
	s_waitcnt vmcnt(0)
; __device__ __forceinline__ unsigned cvt_pk_bf16(float lo, float hi) { unsigned r; asm volatile("v_cvt_pk_bf16_f32 %0, %1, %2" : "=v"(r) : "v"(lo), "v"(hi)); return r; }
;     __device__ __forceinline__ void operator()(const f32x4 (&acc)[2][2][4][2], const Unit& u, int wr, int wc, int fr, int fq) const {
;     ...
;             for (int m = 0; m < 4; ++m) { const int row = row0 + ai * HALF + m * 16; bf16_t* rowp = O + (size_t)row * ldc + col0;
;                 const float rs = 1.0f / sqrtf(rowss[row] * (1.f / 1024.f) + 1e-6f);
; #pragma unroll
;                 for (int bj = 0; bj < 2; ++bj) { const f32x4 v0 = acc[ai][bj][m][0] * rs + bv[bj][0], v1 = acc[ai][bj][m][1] * rs + bv[bj][1];
;                     u32x4 w; w.x = cvt_pk_bf16(v0[0], v0[1]); w.y = cvt_pk_bf16(v0[2], v0[3]); w.z = cvt_pk_bf16(v1[0], v1[1]); w.w = cvt_pk_bf16(v1[2], v1[3]);
;                     *(u32x4*)(rowp + bj * HALF) = w; } }
	v_fmamk_f32 v97, v97, 0x3a800000, v174
	v_mul_f32_e32 v98, 0x4f800000, v97
	v_cmp_gt_f32_e32 vcc, s48, v97
	s_nop 1
	v_cndmask_b32_e32 v100, v97, v98, vcc
	v_sqrt_f32_e32 v101, v100
	v_mad_i64_i32 v[98:99], s[2:3], v128, s47, v[162:163]
	v_ashrrev_i32_e32 v97, 31, v96
	v_add_u32_e32 v102, -1, v101
	v_add_u32_e32 v103, 1, v101
	v_fma_f32 v104, -v102, v101, v100
	v_fma_f32 v105, -v103, v101, v100
	v_cmp_ge_f32_e64 s[2:3], 0, v104
	v_lshl_add_u64 v[98:99], v[98:99], 0, v[166:167]
	s_nop 0
	v_cndmask_b32_e64 v101, v101, v102, s[2:3]
	v_cmp_lt_f32_e64 s[2:3], 0, v105
	s_nop 1
	v_cndmask_b32_e64 v101, v101, v103, s[2:3]
	v_mul_f32_e32 v102, 0x37800000, v101
	v_cndmask_b32_e32 v101, v101, v102, vcc
	v_cmp_class_f32_e32 vcc, v100, v175
	s_nop 1
	v_cndmask_b32_e32 v102, v101, v100, vcc
	v_div_scale_f32 v103, s[2:3], v102, v102, 1.0
	v_rcp_f32_e32 v104, v103
	v_lshl_add_u64 v[100:101], v[96:97], 2, s[68:69]
	v_div_scale_f32 v97, vcc, 1.0, v102, 1.0
	v_fma_f32 v105, -v103, v104, 1.0
	v_fmac_f32_e32 v104, v105, v104
	v_mul_f32_e32 v105, v97, v104
	v_fma_f32 v106, -v103, v105, v97
	v_fmac_f32_e32 v105, v106, v104
	v_fma_f32 v97, -v103, v105, v97
	v_div_fmas_f32 v97, v97, v104, v105
	v_div_fixup_f32 v102, v97, v102, 1.0
	v_pk_fma_f32 v[94:95], v[94:95], v[102:103], v[126:127] op_sel_hi:[1,0,1]
	v_pk_fma_f32 v[92:93], v[92:93], v[102:103], v[124:125] op_sel_hi:[1,0,1]
	v_pk_fma_f32 v[90:91], v[90:91], v[102:103], v[122:123] op_sel_hi:[1,0,1]
	v_pk_fma_f32 v[88:89], v[88:89], v[102:103], v[120:121] op_sel_hi:[1,0,1]
	v_pk_fma_f32 v[86:87], v[86:87], v[102:103], v[118:119] op_sel_hi:[1,0,1]
	v_pk_fma_f32 v[84:85], v[84:85], v[102:103], v[116:117] op_sel_hi:[1,0,1]
	v_pk_fma_f32 v[104:105], v[82:83], v[102:103], v[114:115] op_sel_hi:[1,0,1]
	v_pk_fma_f32 v[102:103], v[80:81], v[102:103], v[112:113] op_sel_hi:[1,0,1]
	v_cvt_pk_bf16_f32 v80, v92, v93
	v_cvt_pk_bf16_f32 v81, v94, v95
	v_cvt_pk_bf16_f32 v82, v88, v89
	v_cvt_pk_bf16_f32 v83, v90, v91
	global_store_dwordx4 v[98:99], v[80:83], off sc1
	s_nop 1
	v_cvt_pk_bf16_f32 v80, v84, v85
	v_cvt_pk_bf16_f32 v81, v86, v87
	v_cvt_pk_bf16_f32 v82, v102, v103
	v_cvt_pk_bf16_f32 v83, v104, v105
	global_store_dwordx4 v[98:99], v[80:83], off offset:256 sc1
	global_load_dword v80, v[100:101], off
	s_waitcnt vmcnt(0)
	v_fmamk_f32 v80, v80, 0x3a800000, v174
	v_mul_f32_e32 v81, 0x4f800000, v80
	v_cmp_gt_f32_e32 vcc, s48, v80
	s_nop 1
	v_cndmask_b32_e32 v82, v80, v81, vcc
	v_sqrt_f32_e32 v83, v82
	v_mad_i64_i32 v[80:81], s[2:3], v96, s47, v[162:163]
	v_lshl_add_u64 v[80:81], v[80:81], 0, v[166:167]
	v_add_u32_e32 v84, -1, v83
	v_add_u32_e32 v85, 1, v83
	v_fma_f32 v86, -v84, v83, v82
	v_fma_f32 v87, -v85, v83, v82
	v_cmp_ge_f32_e64 s[2:3], 0, v86
	s_nop 1
	v_cndmask_b32_e64 v83, v83, v84, s[2:3]
	v_cmp_lt_f32_e64 s[2:3], 0, v87
	s_nop 1
	v_cndmask_b32_e64 v83, v83, v85, s[2:3]
	v_mul_f32_e32 v84, 0x37800000, v83
	v_cndmask_b32_e32 v83, v83, v84, vcc
	v_cmp_class_f32_e32 vcc, v82, v175
	s_nop 1
	v_cndmask_b32_e32 v82, v83, v82, vcc
	v_div_scale_f32 v83, s[2:3], v82, v82, 1.0
	v_rcp_f32_e32 v84, v83
	v_div_scale_f32 v85, vcc, 1.0, v82, 1.0
	v_fma_f32 v86, -v83, v84, 1.0
	v_fmac_f32_e32 v84, v86, v84
	v_mul_f32_e32 v86, v85, v84
	v_fma_f32 v87, -v83, v86, v85
	v_fmac_f32_e32 v86, v87, v84
	v_fma_f32 v83, -v83, v86, v85
	v_div_fmas_f32 v83, v83, v84, v86
	v_div_fixup_f32 v82, v83, v82, 1.0
	v_pk_fma_f32 v[78:79], v[78:79], v[82:83], v[126:127] op_sel_hi:[1,0,1]
	v_pk_fma_f32 v[76:77], v[76:77], v[82:83], v[124:125] op_sel_hi:[1,0,1]
	v_pk_fma_f32 v[74:75], v[74:75], v[82:83], v[122:123] op_sel_hi:[1,0,1]
	v_pk_fma_f32 v[72:73], v[72:73], v[82:83], v[120:121] op_sel_hi:[1,0,1]
	v_pk_fma_f32 v[70:71], v[70:71], v[82:83], v[118:119] op_sel_hi:[1,0,1]
	v_pk_fma_f32 v[68:69], v[68:69], v[82:83], v[116:117] op_sel_hi:[1,0,1]
	v_pk_fma_f32 v[84:85], v[66:67], v[82:83], v[114:115] op_sel_hi:[1,0,1]
	v_pk_fma_f32 v[82:83], v[64:65], v[82:83], v[112:113] op_sel_hi:[1,0,1]
	v_cvt_pk_bf16_f32 v64, v76, v77
	v_cvt_pk_bf16_f32 v65, v78, v79
	v_cvt_pk_bf16_f32 v66, v72, v73
	v_cvt_pk_bf16_f32 v67, v74, v75
	global_store_dwordx4 v[80:81], v[64:67], off sc1
	s_nop 1
	v_cvt_pk_bf16_f32 v64, v68, v69
	v_cvt_pk_bf16_f32 v65, v70, v71
	v_cvt_pk_bf16_f32 v66, v82, v83
	v_cvt_pk_bf16_f32 v67, v84, v85
	global_store_dwordx4 v[80:81], v[64:67], off offset:256 sc1
	global_load_dword v64, v[164:165], off offset:512
	s_waitcnt vmcnt(0)
	v_fmamk_f32 v64, v64, 0x3a800000, v174
	v_mul_f32_e32 v65, 0x4f800000, v64
	v_cmp_gt_f32_e32 vcc, s48, v64
	s_nop 1
	v_cndmask_b32_e32 v66, v64, v65, vcc
	v_sqrt_f32_e32 v67, v66
	v_add_u32_e32 v64, 0x80, v160
	v_mad_i64_i32 v[64:65], s[2:3], v64, s47, v[162:163]
	v_add_u32_e32 v68, -1, v67
	v_add_u32_e32 v69, 1, v67
	v_fma_f32 v70, -v68, v67, v66
	v_fma_f32 v71, -v69, v67, v66
	v_cmp_ge_f32_e64 s[2:3], 0, v70
	v_lshl_add_u64 v[64:65], v[64:65], 0, v[166:167]
	s_nop 0
	v_cndmask_b32_e64 v67, v67, v68, s[2:3]
	v_cmp_lt_f32_e64 s[2:3], 0, v71
	s_nop 1
	v_cndmask_b32_e64 v67, v67, v69, s[2:3]
	v_mul_f32_e32 v68, 0x37800000, v67
	v_cndmask_b32_e32 v67, v67, v68, vcc
	v_cmp_class_f32_e32 vcc, v66, v175
	s_nop 1
	v_cndmask_b32_e32 v66, v67, v66, vcc
	v_div_scale_f32 v67, s[2:3], v66, v66, 1.0
	v_rcp_f32_e32 v68, v67
	v_div_scale_f32 v69, vcc, 1.0, v66, 1.0
	v_fma_f32 v70, -v67, v68, 1.0
	v_fmac_f32_e32 v68, v70, v68
	v_mul_f32_e32 v70, v69, v68
	v_fma_f32 v71, -v67, v70, v69
	v_fmac_f32_e32 v70, v71, v68
	v_fma_f32 v67, -v67, v70, v69
	v_div_fmas_f32 v67, v67, v68, v70
	v_div_fixup_f32 v66, v67, v66, 1.0
	v_pk_fma_f32 v[62:63], v[62:63], v[66:67], v[126:127] op_sel_hi:[1,0,1]
	v_pk_fma_f32 v[60:61], v[60:61], v[66:67], v[124:125] op_sel_hi:[1,0,1]
	v_pk_fma_f32 v[58:59], v[58:59], v[66:67], v[122:123] op_sel_hi:[1,0,1]
	v_pk_fma_f32 v[56:57], v[56:57], v[66:67], v[120:121] op_sel_hi:[1,0,1]
	v_pk_fma_f32 v[54:55], v[54:55], v[66:67], v[118:119] op_sel_hi:[1,0,1]
	v_pk_fma_f32 v[52:53], v[52:53], v[66:67], v[116:117] op_sel_hi:[1,0,1]
	v_pk_fma_f32 v[68:69], v[50:51], v[66:67], v[114:115] op_sel_hi:[1,0,1]
	v_pk_fma_f32 v[66:67], v[48:49], v[66:67], v[112:113] op_sel_hi:[1,0,1]
	v_cvt_pk_bf16_f32 v48, v60, v61
	v_cvt_pk_bf16_f32 v49, v62, v63
	v_cvt_pk_bf16_f32 v50, v56, v57
	v_cvt_pk_bf16_f32 v51, v58, v59
	global_store_dwordx4 v[64:65], v[48:51], off sc1
	s_nop 1
	v_cvt_pk_bf16_f32 v48, v52, v53
	v_cvt_pk_bf16_f32 v49, v54, v55
	v_cvt_pk_bf16_f32 v50, v66, v67
	v_cvt_pk_bf16_f32 v51, v68, v69
	global_store_dwordx4 v[64:65], v[48:51], off offset:256 sc1
	global_load_dword v48, v[164:165], off offset:576
	s_waitcnt vmcnt(0)
; __device__ __forceinline__ unsigned cvt_pk_bf16(float lo, float hi) { unsigned r; asm volatile("v_cvt_pk_bf16_f32 %0, %1, %2" : "=v"(r) : "v"(lo), "v"(hi)); return r; }
;     __device__ __forceinline__ void operator()(const f32x4 (&acc)[2][2][4][2], const Unit& u, int wr, int wc, int fr, int fq) const {
;     ...
;             for (int m = 0; m < 4; ++m) { const int row = row0 + ai * HALF + m * 16; bf16_t* rowp = O + (size_t)row * ldc + col0;
;                 const float rs = 1.0f / sqrtf(rowss[row] * (1.f / 1024.f) + 1e-6f);
; #pragma unroll
;                 for (int bj = 0; bj < 2; ++bj) { const f32x4 v0 = acc[ai][bj][m][0] * rs + bv[bj][0], v1 = acc[ai][bj][m][1] * rs + bv[bj][1];
;                     u32x4 w; w.x = cvt_pk_bf16(v0[0], v0[1]); w.y = cvt_pk_bf16(v0[2], v0[3]); w.z = cvt_pk_bf16(v1[0], v1[1]); w.w = cvt_pk_bf16(v1[2], v1[3]);
;                     *(u32x4*)(rowp + bj * HALF) = w; } }
	v_fmamk_f32 v48, v48, 0x3a800000, v174
	v_mul_f32_e32 v49, 0x4f800000, v48
	v_cmp_gt_f32_e32 vcc, s48, v48
	s_nop 1
	v_cndmask_b32_e32 v50, v48, v49, vcc
	v_sqrt_f32_e32 v51, v50
	v_add_u32_e32 v48, 0x90, v160
	v_mad_i64_i32 v[48:49], s[2:3], v48, s47, v[162:163]
	v_add_u32_e32 v52, -1, v51
	v_add_u32_e32 v53, 1, v51
	v_fma_f32 v54, -v52, v51, v50
	v_fma_f32 v55, -v53, v51, v50
	v_cmp_ge_f32_e64 s[2:3], 0, v54
	v_lshl_add_u64 v[48:49], v[48:49], 0, v[166:167]
	s_nop 0
	v_cndmask_b32_e64 v51, v51, v52, s[2:3]
	v_cmp_lt_f32_e64 s[2:3], 0, v55
	s_nop 1
	v_cndmask_b32_e64 v51, v51, v53, s[2:3]
	v_mul_f32_e32 v52, 0x37800000, v51
	v_cndmask_b32_e32 v51, v51, v52, vcc
	v_cmp_class_f32_e32 vcc, v50, v175
	s_nop 1
	v_cndmask_b32_e32 v50, v51, v50, vcc
	v_div_scale_f32 v51, s[2:3], v50, v50, 1.0
	v_rcp_f32_e32 v52, v51
	v_div_scale_f32 v53, vcc, 1.0, v50, 1.0
	v_fma_f32 v54, -v51, v52, 1.0
	v_fmac_f32_e32 v52, v54, v52
	v_mul_f32_e32 v54, v53, v52
	v_fma_f32 v55, -v51, v54, v53
	v_fmac_f32_e32 v54, v55, v52
	v_fma_f32 v51, -v51, v54, v53
	v_div_fmas_f32 v51, v51, v52, v54
	v_div_fixup_f32 v50, v51, v50, 1.0
	v_pk_fma_f32 v[46:47], v[46:47], v[50:51], v[126:127] op_sel_hi:[1,0,1]
	v_pk_fma_f32 v[44:45], v[44:45], v[50:51], v[124:125] op_sel_hi:[1,0,1]
	v_pk_fma_f32 v[42:43], v[42:43], v[50:51], v[122:123] op_sel_hi:[1,0,1]
	v_pk_fma_f32 v[40:41], v[40:41], v[50:51], v[120:121] op_sel_hi:[1,0,1]
	v_pk_fma_f32 v[38:39], v[38:39], v[50:51], v[118:119] op_sel_hi:[1,0,1]
	v_pk_fma_f32 v[36:37], v[36:37], v[50:51], v[116:117] op_sel_hi:[1,0,1]
	v_pk_fma_f32 v[52:53], v[34:35], v[50:51], v[114:115] op_sel_hi:[1,0,1]
	v_pk_fma_f32 v[50:51], v[32:33], v[50:51], v[112:113] op_sel_hi:[1,0,1]
	v_cvt_pk_bf16_f32 v32, v44, v45
	v_cvt_pk_bf16_f32 v33, v46, v47
	v_cvt_pk_bf16_f32 v34, v40, v41
	v_cvt_pk_bf16_f32 v35, v42, v43
	global_store_dwordx4 v[48:49], v[32:35], off sc1
	s_nop 1
	v_cvt_pk_bf16_f32 v32, v36, v37
	v_cvt_pk_bf16_f32 v33, v38, v39
	v_cvt_pk_bf16_f32 v34, v50, v51
	v_cvt_pk_bf16_f32 v35, v52, v53
	global_store_dwordx4 v[48:49], v[32:35], off offset:256 sc1
	global_load_dword v32, v[164:165], off offset:640
	s_waitcnt vmcnt(0)
	v_fmamk_f32 v32, v32, 0x3a800000, v174
	v_mul_f32_e32 v33, 0x4f800000, v32
	v_cmp_gt_f32_e32 vcc, s48, v32
	s_nop 1
	v_cndmask_b32_e32 v34, v32, v33, vcc
	v_sqrt_f32_e32 v35, v34
	v_add_u32_e32 v32, 0xa0, v160
	v_mad_i64_i32 v[32:33], s[2:3], v32, s47, v[162:163]
	v_add_u32_e32 v36, -1, v35
	v_add_u32_e32 v37, 1, v35
	v_fma_f32 v38, -v36, v35, v34
	v_fma_f32 v39, -v37, v35, v34
	v_cmp_ge_f32_e64 s[2:3], 0, v38
	v_lshl_add_u64 v[32:33], v[32:33], 0, v[166:167]
	s_nop 0
	v_cndmask_b32_e64 v35, v35, v36, s[2:3]
	v_cmp_lt_f32_e64 s[2:3], 0, v39
	s_nop 1
	v_cndmask_b32_e64 v35, v35, v37, s[2:3]
	v_mul_f32_e32 v36, 0x37800000, v35
	v_cndmask_b32_e32 v35, v35, v36, vcc
	v_cmp_class_f32_e32 vcc, v34, v175
	s_nop 1
	v_cndmask_b32_e32 v34, v35, v34, vcc
	v_div_scale_f32 v35, s[2:3], v34, v34, 1.0
	v_rcp_f32_e32 v36, v35
	v_div_scale_f32 v37, vcc, 1.0, v34, 1.0
	v_fma_f32 v38, -v35, v36, 1.0
	v_fmac_f32_e32 v36, v38, v36
	v_mul_f32_e32 v38, v37, v36
	v_fma_f32 v39, -v35, v38, v37
	v_fmac_f32_e32 v38, v39, v36
	v_fma_f32 v35, -v35, v38, v37
	v_div_fmas_f32 v35, v35, v36, v38
	v_div_fixup_f32 v34, v35, v34, 1.0
	v_pk_fma_f32 v[30:31], v[30:31], v[34:35], v[126:127] op_sel_hi:[1,0,1]
	v_pk_fma_f32 v[28:29], v[28:29], v[34:35], v[124:125] op_sel_hi:[1,0,1]
	v_pk_fma_f32 v[26:27], v[26:27], v[34:35], v[122:123] op_sel_hi:[1,0,1]
	v_pk_fma_f32 v[24:25], v[24:25], v[34:35], v[120:121] op_sel_hi:[1,0,1]
	v_pk_fma_f32 v[22:23], v[22:23], v[34:35], v[118:119] op_sel_hi:[1,0,1]
	v_pk_fma_f32 v[20:21], v[20:21], v[34:35], v[116:117] op_sel_hi:[1,0,1]
	v_pk_fma_f32 v[36:37], v[18:19], v[34:35], v[114:115] op_sel_hi:[1,0,1]
	v_pk_fma_f32 v[34:35], v[16:17], v[34:35], v[112:113] op_sel_hi:[1,0,1]
	v_cvt_pk_bf16_f32 v16, v28, v29
	v_cvt_pk_bf16_f32 v17, v30, v31
	v_cvt_pk_bf16_f32 v18, v24, v25
	v_cvt_pk_bf16_f32 v19, v26, v27
	global_store_dwordx4 v[32:33], v[16:19], off sc1
	s_nop 1
	v_cvt_pk_bf16_f32 v16, v20, v21
	v_cvt_pk_bf16_f32 v17, v22, v23
	v_cvt_pk_bf16_f32 v18, v34, v35
	v_cvt_pk_bf16_f32 v19, v36, v37
	global_store_dwordx4 v[32:33], v[16:19], off offset:256 sc1
	global_load_dword v16, v[164:165], off offset:704
	s_nop 0
	v_add_u32_e32 v17, 0xb0, v160
	s_waitcnt vmcnt(0)
	v_fmamk_f32 v16, v16, 0x3a800000, v174
	v_mul_f32_e32 v18, 0x4f800000, v16
	v_cmp_gt_f32_e32 vcc, s48, v16
	s_nop 1
	v_cndmask_b32_e32 v18, v16, v18, vcc
	v_sqrt_f32_e32 v19, v18
	v_mad_i64_i32 v[16:17], s[2:3], v17, s47, v[162:163]
	v_lshl_add_u64 v[16:17], v[16:17], 0, v[166:167]
	v_add_u32_e32 v20, -1, v19
	v_add_u32_e32 v21, 1, v19
	v_fma_f32 v22, -v20, v19, v18
	v_fma_f32 v23, -v21, v19, v18
	v_cmp_ge_f32_e64 s[2:3], 0, v22
	s_nop 1
	v_cndmask_b32_e64 v19, v19, v20, s[2:3]
	v_cmp_lt_f32_e64 s[2:3], 0, v23
	s_nop 1
	v_cndmask_b32_e64 v19, v19, v21, s[2:3]
	v_mul_f32_e32 v20, 0x37800000, v19
	v_cndmask_b32_e32 v19, v19, v20, vcc
	v_cmp_class_f32_e32 vcc, v18, v175
	s_nop 1
	v_cndmask_b32_e32 v18, v19, v18, vcc
	v_div_scale_f32 v19, s[2:3], v18, v18, 1.0
	v_rcp_f32_e32 v20, v19
	v_div_scale_f32 v21, vcc, 1.0, v18, 1.0
	v_fma_f32 v22, -v19, v20, 1.0
	v_fmac_f32_e32 v20, v22, v20
	v_mul_f32_e32 v22, v21, v20
	v_fma_f32 v23, -v19, v22, v21
	v_fmac_f32_e32 v22, v23, v20
	v_fma_f32 v19, -v19, v22, v21
	v_div_fmas_f32 v19, v19, v20, v22
	v_div_fixup_f32 v18, v19, v18, 1.0
	s_andn2_b64 vcc, exec, s[0:1]
	v_pk_fma_f32 v[14:15], v[14:15], v[18:19], v[126:127] op_sel_hi:[1,0,1]
	v_pk_fma_f32 v[12:13], v[12:13], v[18:19], v[124:125] op_sel_hi:[1,0,1]
	v_pk_fma_f32 v[10:11], v[10:11], v[18:19], v[122:123] op_sel_hi:[1,0,1]
	v_pk_fma_f32 v[8:9], v[8:9], v[18:19], v[120:121] op_sel_hi:[1,0,1]
	v_pk_fma_f32 v[6:7], v[6:7], v[18:19], v[118:119] op_sel_hi:[1,0,1]
	v_pk_fma_f32 v[4:5], v[4:5], v[18:19], v[116:117] op_sel_hi:[1,0,1]
	v_pk_fma_f32 v[20:21], v[2:3], v[18:19], v[114:115] op_sel_hi:[1,0,1]
	v_pk_fma_f32 v[18:19], v[0:1], v[18:19], v[112:113] op_sel_hi:[1,0,1]
	v_cvt_pk_bf16_f32 v0, v12, v13
	v_cvt_pk_bf16_f32 v1, v14, v15
	v_cvt_pk_bf16_f32 v2, v8, v9
	v_cvt_pk_bf16_f32 v3, v10, v11
	s_mov_b64 s[0:1], -1
	global_store_dwordx4 v[16:17], v[0:3], off sc1
	s_nop 1
	v_cvt_pk_bf16_f32 v0, v4, v5
	v_cvt_pk_bf16_f32 v1, v6, v7
	v_cvt_pk_bf16_f32 v2, v18, v19
	v_cvt_pk_bf16_f32 v3, v20, v21
	global_store_dwordx4 v[16:17], v[0:3], off offset:256 sc1
	s_cbranch_vccnz .LBB0_625
	s_andn2_b64 vcc, exec, s[6:7]
	s_cbranch_vccnz .LBB0_624
	s_barrier
	s_branch .LBB0_624

;     __device__ __forceinline__ void operator()(const f32x4 (&acc)[2][2][4][2], const Unit& u, int wr, int wc, int fr, int fq) const {
;         const int row0 = u.pm * BM + wr * 64 + fr; const int col0 = u.pn * BM + wc * 32 + 8 * fq;
;         const float* bp = bias + (size_t)((u.pn * BM) / 8192) * 4096 + boff;
;         f32x4 rs[2][2];
; #pragma unroll
;         for (int bj = 0; bj < 2; ++bj)
; #pragma unroll
;             for (int n = 0; n < 2; ++n) { const f32x4 q = *(const f32x4*)(rowss + col0 + bj * HALF + 4 * n);
; #pragma unroll
;                 for (int e = 0; e < 4; ++e) rs[bj][n][e] = 1.0f / sqrtf(q[e] * (1.f / 1024.f) + 1e-6f); }
.LBB0_656:
	v_lshl_add_u32 v156, s10, 8, v168
	v_ashrrev_i32_e32 v157, 31, v156
	v_lshl_add_u64 v[154:155], v[156:157], 2, s[68:69]
	global_load_dwordx4 v[150:153], v[154:155], off
	global_load_dwordx4 v[130:133], v[154:155], off offset:16
	s_ashr_i32 s2, s10, 31
	s_lshr_b32 s2, s2, 27
	s_add_i32 s2, s10, s2
	s_ashr_i32 s2, s2, 5
	s_ashr_i32 s3, s2, 31
	s_lshl_b64 s[40:41], s[2:3], 14
	s_waitcnt vmcnt(0)
	v_fmamk_f32 v128, v150, 0x3a800000, v172
	v_fmamk_f32 v129, v151, 0x3a800000, v172
	v_fmamk_f32 v150, v152, 0x3a800000, v172
	v_fmamk_f32 v151, v153, 0x3a800000, v172
	v_mul_f32_e32 v152, 0x4f800000, v128
	v_cmp_gt_f32_e32 vcc, s54, v128
	v_mul_f32_e32 v153, 0x4f800000, v129
	v_mul_f32_e32 v159, 0x4f800000, v151
	v_cndmask_b32_e32 v128, v128, v152, vcc
	v_cmp_gt_f32_e64 s[2:3], s54, v129
	v_cmp_gt_f32_e64 s[8:9], s54, v151
	v_mul_f32_e32 v158, 0x4f800000, v150
	v_cndmask_b32_e64 v129, v129, v153, s[2:3]
	v_cmp_gt_f32_e64 s[6:7], s54, v150
	v_cndmask_b32_e64 v152, v151, v159, s[8:9]
	v_sqrt_f32_e32 v151, v128
	v_cndmask_b32_e64 v150, v150, v158, s[6:7]
	v_sqrt_f32_e32 v153, v129
	v_sqrt_f32_e32 v158, v150
	v_sqrt_f32_e32 v159, v152
	v_add_u32_e32 v160, -1, v151
	v_add_u32_e32 v162, -1, v153
	v_fma_f32 v176, -v160, v151, v128
	v_add_u32_e32 v161, 1, v151
	v_add_u32_e32 v164, -1, v158
	v_fma_f32 v178, -v162, v153, v129
	v_cmp_ge_f32_e64 s[10:11], 0, v176
	v_add_u32_e32 v163, 1, v153
	v_add_u32_e32 v174, -1, v159
	v_fma_f32 v177, -v161, v151, v128
	v_fma_f32 v180, -v164, v158, v150
	v_cndmask_b32_e64 v151, v151, v160, s[10:11]
	v_cmp_ge_f32_e64 s[10:11], 0, v178
	v_add_u32_e32 v165, 1, v158
	v_fma_f32 v179, -v163, v153, v129
	v_fma_f32 v182, -v174, v159, v152
	v_cndmask_b32_e64 v153, v153, v162, s[10:11]
	v_cmp_ge_f32_e64 s[10:11], 0, v180
	v_fma_f32 v181, -v165, v158, v150
	v_add_u32_e32 v175, 1, v159
	v_cndmask_b32_e64 v158, v158, v164, s[10:11]
	v_cmp_ge_f32_e64 s[10:11], 0, v182
	v_fmamk_f32 v130, v130, 0x3a800000, v172
	v_fmamk_f32 v132, v132, 0x3a800000, v172
	v_cndmask_b32_e64 v160, v159, v174, s[10:11]
	v_cmp_lt_f32_e64 s[10:11], 0, v177
	v_fmamk_f32 v133, v133, 0x3a800000, v172
	s_nop 0
	v_cndmask_b32_e64 v151, v151, v161, s[10:11]
	v_cmp_lt_f32_e64 s[10:11], 0, v179
	v_mul_f32_e32 v161, 0x37800000, v151
	v_cndmask_b32_e32 v151, v151, v161, vcc
	v_cndmask_b32_e64 v153, v153, v163, s[10:11]
	v_cmp_lt_f32_e64 s[10:11], 0, v181
	v_mul_f32_e32 v162, 0x37800000, v153
	v_cmp_class_f32_e32 vcc, v128, v173
	v_cndmask_b32_e64 v158, v158, v165, s[10:11]
	v_mul_f32_e32 v163, 0x37800000, v158
	v_cndmask_b32_e64 v153, v153, v162, s[2:3]
	v_cndmask_b32_e32 v128, v151, v128, vcc
	v_cmp_class_f32_e32 vcc, v129, v173
	v_cndmask_b32_e64 v158, v158, v163, s[6:7]
	s_nop 0
	v_cndmask_b32_e32 v129, v153, v129, vcc
	v_cmp_class_f32_e32 vcc, v150, v173
	s_nop 1
	v_cndmask_b32_e32 v153, v158, v150, vcc
	v_div_scale_f32 v150, s[2:3], v128, v128, 1.0
	v_div_scale_f32 v158, s[2:3], v129, v129, 1.0
	v_rcp_f32_e32 v163, v150
	v_rcp_f32_e32 v164, v158
	v_div_scale_f32 v151, vcc, 1.0, v128, 1.0
	v_fma_f32 v176, -v150, v163, 1.0
	v_fma_f32 v177, -v158, v164, 1.0
	v_fmac_f32_e32 v163, v176, v163
	v_div_scale_f32 v161, s[2:3], 1.0, v129, 1.0
	v_fmac_f32_e32 v164, v177, v164
	v_mul_f32_e32 v176, v151, v163
	v_mul_f32_e32 v177, v161, v164
	v_fma_f32 v179, -v150, v176, v151
	v_fma_f32 v180, -v158, v177, v161
	v_fmac_f32_e32 v176, v179, v163
	v_fmac_f32_e32 v177, v180, v164
	v_fma_f32 v150, -v150, v176, v151
	v_fma_f32 v151, -v158, v177, v161
	v_div_fmas_f32 v150, v150, v163, v176
	s_mov_b64 vcc, s[2:3]
	v_div_scale_f32 v162, s[6:7], v153, v153, 1.0
	v_div_fixup_f32 v150, v150, v128, 1.0
	v_div_fmas_f32 v128, v151, v164, v177
	v_rcp_f32_e32 v165, v162
	v_div_fixup_f32 v151, v128, v129, 1.0
	v_fma_f32 v128, -v175, v159, v152
	v_cmp_lt_f32_e32 vcc, 0, v128
	v_fma_f32 v178, -v162, v165, 1.0
	v_div_scale_f32 v174, s[6:7], 1.0, v153, 1.0
	v_cndmask_b32_e32 v128, v160, v175, vcc
	v_mul_f32_e32 v129, 0x37800000, v128
	v_cndmask_b32_e64 v128, v128, v129, s[8:9]
	v_cmp_class_f32_e32 vcc, v152, v173
	v_fmac_f32_e32 v165, v178, v165
	v_mul_f32_e32 v178, v174, v165
	v_cndmask_b32_e32 v128, v128, v152, vcc
	v_div_scale_f32 v129, s[2:3], v128, v128, 1.0
	v_fma_f32 v181, -v162, v178, v174
	v_rcp_f32_e32 v159, v129
	v_fmac_f32_e32 v178, v181, v165
	v_fma_f32 v158, -v162, v178, v174
	s_mov_b64 vcc, s[6:7]
	v_div_fmas_f32 v152, v158, v165, v178
	v_mul_f32_e32 v160, 0x4f800000, v130
	v_cmp_gt_f32_e64 s[2:3], s54, v130
	v_div_fixup_f32 v152, v152, v153, 1.0
	v_fma_f32 v153, -v129, v159, 1.0
	v_cndmask_b32_e64 v130, v130, v160, s[2:3]
	v_fmac_f32_e32 v159, v153, v159
	v_div_scale_f32 v153, vcc, 1.0, v128, 1.0
	v_sqrt_f32_e32 v160, v130
	v_mul_f32_e32 v158, v153, v159
	v_fma_f32 v161, -v129, v158, v153
	v_fmac_f32_e32 v158, v161, v159
	v_fma_f32 v129, -v129, v158, v153
	v_add_u32_e32 v153, -1, v160
	v_fma_f32 v161, -v153, v160, v130
	v_cmp_ge_f32_e64 s[6:7], 0, v161
	v_add_u32_e32 v161, 1, v160
	v_div_fmas_f32 v129, v129, v159, v158
	v_cndmask_b32_e64 v153, v160, v153, s[6:7]
	v_fma_f32 v160, -v161, v160, v130
	v_cmp_lt_f32_e64 s[6:7], 0, v160
	s_nop 1
	v_cndmask_b32_e64 v153, v153, v161, s[6:7]
	v_mul_f32_e32 v160, 0x37800000, v153
	v_cndmask_b32_e64 v153, v153, v160, s[2:3]
	v_cmp_class_f32_e64 s[2:3], v130, v173
	s_nop 1
	v_cndmask_b32_e64 v162, v153, v130, s[2:3]
	v_div_scale_f32 v130, s[2:3], v162, v162, 1.0
	v_rcp_f32_e32 v163, v130
	v_div_fixup_f32 v153, v129, v128, 1.0
	v_fmamk_f32 v129, v131, 0x3a800000, v172
	v_mul_f32_e32 v131, 0x4f800000, v129
	v_cmp_gt_f32_e64 s[2:3], s54, v129
	v_fma_f32 v128, -v130, v163, 1.0
	v_fmac_f32_e32 v163, v128, v163
	v_cndmask_b32_e64 v165, v129, v131, s[2:3]
	v_div_scale_f32 v128, vcc, 1.0, v162, 1.0
	v_sqrt_f32_e32 v129, v165
	v_mul_f32_e32 v164, v128, v163
	v_fma_f32 v131, -v130, v164, v128
	v_fmac_f32_e32 v164, v131, v163
	v_fma_f32 v174, -v130, v164, v128
	v_add_u32_e32 v128, -1, v129
	v_fma_f32 v130, -v128, v129, v165
	v_cmp_ge_f32_e64 s[6:7], 0, v130
	v_add_u32_e32 v176, 1, v129
	v_fma_f32 v177, -v176, v129, v165
	v_cndmask_b32_e64 v175, v129, v128, s[6:7]
	global_load_dwordx4 v[128:131], v[154:155], off offset:528
	global_load_dwordx4 v[158:161], v[154:155], off offset:512
	v_cmp_lt_f32_e64 s[6:7], 0, v177
	s_waitcnt vmcnt(1)
;     __device__ __forceinline__ void operator()(const f32x4 (&acc)[2][2][4][2], const Unit& u, int wr, int wc, int fr, int fq) const {
;     ...
;         for (int bj = 0; bj < 2; ++bj)
; #pragma unroll
;             for (int n = 0; n < 2; ++n) { const f32x4 q = *(const f32x4*)(rowss + col0 + bj * HALF + 4 * n);
; #pragma unroll
;                 for (int e = 0; e < 4; ++e) rs[bj][n][e] = 1.0f / sqrtf(q[e] * (1.f / 1024.f) + 1e-6f); }
	v_fmamk_f32 v128, v128, 0x3a800000, v172
	v_cndmask_b32_e64 v154, v175, v176, s[6:7]
	v_mul_f32_e32 v155, 0x37800000, v154
	v_cndmask_b32_e64 v154, v154, v155, s[2:3]
	v_cmp_class_f32_e64 s[2:3], v165, v173
	s_waitcnt vmcnt(0)
	v_fmamk_f32 v158, v158, 0x3a800000, v172
	v_fmamk_f32 v159, v159, 0x3a800000, v172
	v_cndmask_b32_e64 v155, v154, v165, s[2:3]
	v_div_scale_f32 v165, s[2:3], v155, v155, 1.0
	v_rcp_f32_e32 v175, v165
	v_div_fmas_f32 v154, v174, v163, v164
	v_mul_f32_e32 v164, 0x4f800000, v132
	v_cmp_gt_f32_e64 s[2:3], s54, v132
	v_div_fixup_f32 v154, v154, v162, 1.0
	v_fma_f32 v162, -v165, v175, 1.0
	v_cndmask_b32_e64 v132, v132, v164, s[2:3]
	v_fmac_f32_e32 v175, v162, v175
	v_div_scale_f32 v162, vcc, 1.0, v155, 1.0
	v_sqrt_f32_e32 v164, v132
	v_mul_f32_e32 v163, v162, v175
	v_fma_f32 v174, -v165, v163, v162
	v_fmac_f32_e32 v163, v174, v175
	v_fma_f32 v162, -v165, v163, v162
	v_add_u32_e32 v165, -1, v164
	v_fma_f32 v174, -v165, v164, v132
	v_cmp_ge_f32_e64 s[6:7], 0, v174
	v_add_u32_e32 v174, 1, v164
	v_div_fmas_f32 v162, v162, v175, v163
	v_cndmask_b32_e64 v165, v164, v165, s[6:7]
	v_fma_f32 v164, -v174, v164, v132
	v_cmp_lt_f32_e64 s[6:7], 0, v164
	v_div_fixup_f32 v155, v162, v155, 1.0
	v_fmamk_f32 v160, v160, 0x3a800000, v172
	v_cndmask_b32_e64 v164, v165, v174, s[6:7]
	v_mul_f32_e32 v165, 0x37800000, v164
	v_cndmask_b32_e64 v164, v164, v165, s[2:3]
	v_cmp_class_f32_e64 s[2:3], v132, v173
	v_mul_f32_e32 v174, 0x4f800000, v133
	v_fmamk_f32 v161, v161, 0x3a800000, v172
	v_cndmask_b32_e64 v132, v164, v132, s[2:3]
	v_div_scale_f32 v164, s[2:3], v132, v132, 1.0
	v_rcp_f32_e32 v165, v164
	v_cmp_gt_f32_e64 s[2:3], s54, v133
	v_fmamk_f32 v129, v129, 0x3a800000, v172
	v_fmamk_f32 v130, v130, 0x3a800000, v172
	v_fma_f32 v162, -v164, v165, 1.0
	v_cndmask_b32_e64 v133, v133, v174, s[2:3]
	v_fmac_f32_e32 v165, v162, v165
	v_div_scale_f32 v162, vcc, 1.0, v132, 1.0
	v_sqrt_f32_e32 v174, v133
	v_mul_f32_e32 v163, v162, v165
	v_fma_f32 v175, -v164, v163, v162
	v_fmac_f32_e32 v163, v175, v165
	v_fma_f32 v162, -v164, v163, v162
	v_add_u32_e32 v164, -1, v174
	v_fma_f32 v175, -v164, v174, v133
	v_cmp_ge_f32_e64 s[6:7], 0, v175
	v_add_u32_e32 v175, 1, v174
	v_div_fmas_f32 v162, v162, v165, v163
	v_cndmask_b32_e64 v164, v174, v164, s[6:7]
	v_fma_f32 v174, -v175, v174, v133
	v_cmp_lt_f32_e64 s[6:7], 0, v174
	v_mul_f32_e32 v165, 0x4f800000, v158
	v_div_fixup_f32 v132, v162, v132, 1.0
	v_cndmask_b32_e64 v164, v164, v175, s[6:7]
	v_mul_f32_e32 v174, 0x37800000, v164
	v_cndmask_b32_e64 v164, v164, v174, s[2:3]
	v_cmp_class_f32_e64 s[2:3], v133, v173
	v_fmamk_f32 v131, v131, 0x3a800000, v172
	s_nop 0
	v_cndmask_b32_e64 v133, v164, v133, s[2:3]
	v_div_scale_f32 v164, s[2:3], v133, v133, 1.0
	v_rcp_f32_e32 v174, v164
	v_cmp_gt_f32_e64 s[2:3], s54, v158
	v_fma_f32 v162, -v164, v174, 1.0
	s_nop 0
	v_cndmask_b32_e64 v158, v158, v165, s[2:3]
	v_fmac_f32_e32 v174, v162, v174
	v_div_scale_f32 v162, vcc, 1.0, v133, 1.0
	v_sqrt_f32_e32 v165, v158
	v_mul_f32_e32 v163, v162, v174
	v_fma_f32 v175, -v164, v163, v162
	v_fmac_f32_e32 v163, v175, v174
	v_fma_f32 v162, -v164, v163, v162
	v_add_u32_e32 v164, -1, v165
	v_fma_f32 v175, -v164, v165, v158
	v_cmp_ge_f32_e64 s[6:7], 0, v175
	v_add_u32_e32 v175, 1, v165
	v_div_fmas_f32 v162, v162, v174, v163
	v_cndmask_b32_e64 v164, v165, v164, s[6:7]
	v_fma_f32 v165, -v175, v165, v158
	v_cmp_lt_f32_e64 s[6:7], 0, v165
	v_mul_f32_e32 v174, 0x4f800000, v159
	v_div_fixup_f32 v133, v162, v133, 1.0
	v_cndmask_b32_e64 v164, v164, v175, s[6:7]
	v_mul_f32_e32 v165, 0x37800000, v164
	v_cndmask_b32_e64 v164, v164, v165, s[2:3]
	v_cmp_class_f32_e64 s[2:3], v158, v173
	s_nop 1
	v_cndmask_b32_e64 v158, v164, v158, s[2:3]
	v_div_scale_f32 v164, s[2:3], v158, v158, 1.0
	v_rcp_f32_e32 v165, v164
	v_cmp_gt_f32_e64 s[2:3], s54, v159
	v_fma_f32 v162, -v164, v165, 1.0
	s_nop 0
	v_cndmask_b32_e64 v159, v159, v174, s[2:3]
	v_fmac_f32_e32 v165, v162, v165
	v_div_scale_f32 v162, vcc, 1.0, v158, 1.0
	v_sqrt_f32_e32 v174, v159
	v_mul_f32_e32 v163, v162, v165
	v_fma_f32 v175, -v164, v163, v162
	v_fmac_f32_e32 v163, v175, v165
	v_fma_f32 v162, -v164, v163, v162
	v_add_u32_e32 v164, -1, v174
	v_fma_f32 v175, -v164, v174, v159
	v_cmp_ge_f32_e64 s[6:7], 0, v175
	v_add_u32_e32 v175, 1, v174
	v_div_fmas_f32 v162, v162, v165, v163
	v_cndmask_b32_e64 v164, v174, v164, s[6:7]
	v_fma_f32 v174, -v175, v174, v159
	v_cmp_lt_f32_e64 s[6:7], 0, v174
	v_mul_f32_e32 v165, 0x4f800000, v160
	v_div_fixup_f32 v158, v162, v158, 1.0
	v_cndmask_b32_e64 v164, v164, v175, s[6:7]
	v_mul_f32_e32 v174, 0x37800000, v164
	v_cndmask_b32_e64 v164, v164, v174, s[2:3]
	v_cmp_class_f32_e64 s[2:3], v159, v173
	s_nop 1
	v_cndmask_b32_e64 v159, v164, v159, s[2:3]
	v_div_scale_f32 v164, s[2:3], v159, v159, 1.0
	v_rcp_f32_e32 v174, v164
	v_cmp_gt_f32_e64 s[2:3], s54, v160
	v_fma_f32 v162, -v164, v174, 1.0
	s_nop 0
	v_cndmask_b32_e64 v160, v160, v165, s[2:3]
	v_fmac_f32_e32 v174, v162, v174
	v_div_scale_f32 v162, vcc, 1.0, v159, 1.0
	v_sqrt_f32_e32 v165, v160
	v_mul_f32_e32 v163, v162, v174
	v_fma_f32 v175, -v164, v163, v162
	v_fmac_f32_e32 v163, v175, v174
	v_fma_f32 v162, -v164, v163, v162
	v_add_u32_e32 v164, -1, v165
	v_fma_f32 v175, -v164, v165, v160
	v_cmp_ge_f32_e64 s[6:7], 0, v175
	v_add_u32_e32 v175, 1, v165
	v_div_fmas_f32 v162, v162, v174, v163
	v_cndmask_b32_e64 v164, v165, v164, s[6:7]
	v_fma_f32 v165, -v175, v165, v160
	v_cmp_lt_f32_e64 s[6:7], 0, v165
	v_mul_f32_e32 v174, 0x4f800000, v161
	v_div_fixup_f32 v159, v162, v159, 1.0
	v_cndmask_b32_e64 v164, v164, v175, s[6:7]
	v_mul_f32_e32 v165, 0x37800000, v164
	v_cndmask_b32_e64 v164, v164, v165, s[2:3]
	v_cmp_class_f32_e64 s[2:3], v160, v173
;     __device__ __forceinline__ void operator()(const f32x4 (&acc)[2][2][4][2], const Unit& u, int wr, int wc, int fr, int fq) const {
;     ...
;         for (int bj = 0; bj < 2; ++bj)
; #pragma unroll
;             for (int n = 0; n < 2; ++n) { const f32x4 q = *(const f32x4*)(rowss + col0 + bj * HALF + 4 * n);
; #pragma unroll
;                 for (int e = 0; e < 4; ++e) rs[bj][n][e] = 1.0f / sqrtf(q[e] * (1.f / 1024.f) + 1e-6f); }
; #pragma unroll
;         for (int ai = 0; ai < 2; ++ai)
; #pragma unroll
;             for (int m = 0; m < 4; ++m) { const int r = row0 + ai * HALF + m * 16; bf16_t* rowp = O + (size_t)r * ldc + col0; const float bb = bp[r];
	s_nop 1
	v_cndmask_b32_e64 v160, v164, v160, s[2:3]
	v_div_scale_f32 v164, s[2:3], v160, v160, 1.0
	v_rcp_f32_e32 v165, v164
	v_cmp_gt_f32_e64 s[2:3], s54, v161
	v_fma_f32 v162, -v164, v165, 1.0
	s_nop 0
	v_cndmask_b32_e64 v161, v161, v174, s[2:3]
	v_fmac_f32_e32 v165, v162, v165
	v_div_scale_f32 v162, vcc, 1.0, v160, 1.0
	v_sqrt_f32_e32 v174, v161
	v_mul_f32_e32 v163, v162, v165
	v_fma_f32 v175, -v164, v163, v162
	v_fmac_f32_e32 v163, v175, v165
	v_fma_f32 v162, -v164, v163, v162
	v_add_u32_e32 v164, -1, v174
	v_fma_f32 v175, -v164, v174, v161
	v_cmp_ge_f32_e64 s[6:7], 0, v175
	v_add_u32_e32 v175, 1, v174
	v_div_fmas_f32 v162, v162, v165, v163
	v_cndmask_b32_e64 v164, v174, v164, s[6:7]
	v_fma_f32 v174, -v175, v174, v161
	v_cmp_lt_f32_e64 s[6:7], 0, v174
	v_mul_f32_e32 v165, 0x4f800000, v128
	v_div_fixup_f32 v160, v162, v160, 1.0
	v_cndmask_b32_e64 v164, v164, v175, s[6:7]
	v_mul_f32_e32 v174, 0x37800000, v164
	v_cndmask_b32_e64 v164, v164, v174, s[2:3]
	v_cmp_class_f32_e64 s[2:3], v161, v173
	s_nop 1
	v_cndmask_b32_e64 v161, v164, v161, s[2:3]
	v_div_scale_f32 v164, s[2:3], v161, v161, 1.0
	v_rcp_f32_e32 v174, v164
	v_cmp_gt_f32_e64 s[2:3], s54, v128
	v_fma_f32 v162, -v164, v174, 1.0
	s_nop 0
	v_cndmask_b32_e64 v128, v128, v165, s[2:3]
	v_fmac_f32_e32 v174, v162, v174
	v_div_scale_f32 v162, vcc, 1.0, v161, 1.0
	v_sqrt_f32_e32 v165, v128
	v_mul_f32_e32 v163, v162, v174
	v_fma_f32 v175, -v164, v163, v162
	v_fmac_f32_e32 v163, v175, v174
	v_fma_f32 v162, -v164, v163, v162
	v_add_u32_e32 v164, -1, v165
	v_fma_f32 v175, -v164, v165, v128
	v_cmp_ge_f32_e64 s[6:7], 0, v175
	v_add_u32_e32 v175, 1, v165
	v_div_fmas_f32 v162, v162, v174, v163
	v_cndmask_b32_e64 v164, v165, v164, s[6:7]
	v_fma_f32 v165, -v175, v165, v128
	v_cmp_lt_f32_e64 s[6:7], 0, v165
	v_mul_f32_e32 v163, 0x4f800000, v129
	v_div_fixup_f32 v161, v162, v161, 1.0
	v_cndmask_b32_e64 v164, v164, v175, s[6:7]
	v_mul_f32_e32 v165, 0x37800000, v164
	v_cndmask_b32_e64 v164, v164, v165, s[2:3]
	v_cmp_class_f32_e64 s[2:3], v128, v173
	s_nop 1
	v_cndmask_b32_e64 v128, v164, v128, s[2:3]
	v_div_scale_f32 v164, s[2:3], v128, v128, 1.0
	v_rcp_f32_e32 v175, v164
	v_cmp_gt_f32_e64 s[2:3], s54, v129
	v_fma_f32 v162, -v164, v175, 1.0
	s_nop 0
	v_cndmask_b32_e64 v129, v129, v163, s[2:3]
	v_fmac_f32_e32 v175, v162, v175
	v_div_scale_f32 v162, vcc, 1.0, v128, 1.0
	v_sqrt_f32_e32 v163, v129
	v_mul_f32_e32 v176, v162, v175
	v_fma_f32 v165, -v164, v176, v162
	v_fmac_f32_e32 v176, v165, v175
	v_fma_f32 v177, -v164, v176, v162
	v_add_u32_e32 v162, -1, v163
	v_fma_f32 v164, -v162, v163, v129
	v_cmp_ge_f32_e64 s[6:7], 0, v164
	v_add_u32_e32 v164, 1, v163
	v_div_fmas_f32 v175, v177, v175, v176
	v_cndmask_b32_e64 v162, v163, v162, s[6:7]
	v_fma_f32 v163, -v164, v163, v129
	v_cmp_lt_f32_e64 s[6:7], 0, v163
	v_mul_f32_e32 v177, 0x4f800000, v130
	v_div_fixup_f32 v128, v175, v128, 1.0
	v_cndmask_b32_e64 v162, v162, v164, s[6:7]
	v_mul_f32_e32 v163, 0x37800000, v162
	v_cndmask_b32_e64 v162, v162, v163, s[2:3]
	v_cmp_class_f32_e64 s[2:3], v129, v173
	v_lshl_add_u32 v164, s38, 8, v166
	v_ashrrev_i32_e32 v165, 31, v164
	v_cndmask_b32_e64 v129, v162, v129, s[2:3]
	v_div_scale_f32 v178, s[2:3], v129, v129, 1.0
	s_add_u32 s2, s90, s40
	s_addc_u32 s3, s91, s41
	s_add_u32 s8, s2, 0x3000
	s_addc_u32 s9, s3, 0
	v_lshl_add_u64 v[162:163], v[164:165], 2, s[8:9]
	global_load_dword v174, v[162:163], off
	v_rcp_f32_e32 v179, v178
	v_cmp_gt_f32_e64 s[2:3], s54, v130
	v_fma_f32 v175, -v178, v179, 1.0
	s_nop 0
	v_cndmask_b32_e64 v130, v130, v177, s[2:3]
	v_fmac_f32_e32 v179, v175, v179
	v_div_scale_f32 v175, vcc, 1.0, v129, 1.0
	v_sqrt_f32_e32 v177, v130
	v_mul_f32_e32 v176, v175, v179
	v_fma_f32 v180, -v178, v176, v175
	v_fmac_f32_e32 v176, v180, v179
	v_fma_f32 v175, -v178, v176, v175
	v_add_u32_e32 v178, -1, v177
	v_fma_f32 v180, -v178, v177, v130
	v_cmp_ge_f32_e64 s[6:7], 0, v180
	v_add_u32_e32 v180, 1, v177
	v_div_fmas_f32 v175, v175, v179, v176
	v_cndmask_b32_e64 v178, v177, v178, s[6:7]
	v_fma_f32 v177, -v180, v177, v130
	v_cmp_lt_f32_e64 s[6:7], 0, v177
	v_mul_f32_e32 v179, 0x4f800000, v131
	v_div_fixup_f32 v129, v175, v129, 1.0
	v_cndmask_b32_e64 v177, v178, v180, s[6:7]
	v_mul_f32_e32 v178, 0x37800000, v177
	v_cndmask_b32_e64 v177, v177, v178, s[2:3]
	v_cmp_class_f32_e64 s[2:3], v130, v173
	s_nop 1
	v_cndmask_b32_e64 v130, v177, v130, s[2:3]
	v_div_scale_f32 v177, s[2:3], v130, v130, 1.0
	v_rcp_f32_e32 v178, v177
	v_cmp_gt_f32_e64 s[2:3], s54, v131
	v_fma_f32 v175, -v177, v178, 1.0
	s_nop 0
	v_cndmask_b32_e64 v131, v131, v179, s[2:3]
	v_fmac_f32_e32 v178, v175, v178
	v_div_scale_f32 v175, vcc, 1.0, v130, 1.0
	v_sqrt_f32_e32 v179, v131
	v_mul_f32_e32 v176, v175, v178
	v_fma_f32 v180, -v177, v176, v175
	v_fmac_f32_e32 v176, v180, v178
	v_fma_f32 v175, -v177, v176, v175
	v_add_u32_e32 v177, -1, v179
	v_fma_f32 v180, -v177, v179, v131
	v_cmp_ge_f32_e64 s[6:7], 0, v180
	v_add_u32_e32 v180, 1, v179
	v_div_fmas_f32 v175, v175, v178, v176
	v_cndmask_b32_e64 v177, v179, v177, s[6:7]
	v_fma_f32 v179, -v180, v179, v131
	v_cmp_lt_f32_e64 s[6:7], 0, v179
	v_div_fixup_f32 v130, v175, v130, 1.0
	s_nop 0
	v_cndmask_b32_e64 v177, v177, v180, s[6:7]
	v_mul_f32_e32 v179, 0x37800000, v177
	v_cndmask_b32_e64 v177, v177, v179, s[2:3]
	v_cmp_class_f32_e64 s[2:3], v131, v173
	s_nop 1
	v_cndmask_b32_e64 v131, v177, v131, s[2:3]
	v_div_scale_f32 v177, s[2:3], v131, v131, 1.0
	v_rcp_f32_e32 v179, v177
	s_nop 0
	v_fma_f32 v175, -v177, v179, 1.0
	v_fmac_f32_e32 v179, v175, v179
	v_div_scale_f32 v175, vcc, 1.0, v131, 1.0
	v_mul_f32_e32 v176, v175, v179
	v_fma_f32 v178, -v177, v176, v175
	v_fmac_f32_e32 v176, v178, v179
	v_fma_f32 v175, -v177, v176, v175
	v_div_fmas_f32 v175, v175, v179, v176
	v_lshlrev_b64 v[176:177], 16, v[164:165]
	v_lshl_add_u64 v[176:177], s[80:81], 0, v[176:177]
	v_lshlrev_b64 v[178:179], 1, v[156:157]
	v_div_fixup_f32 v131, v175, v131, 1.0
	v_lshl_add_u64 v[156:157], v[176:177], 0, v[178:179]
	s_waitcnt vmcnt(0)
; __device__ __forceinline__ unsigned cvt_pk_bf16(float lo, float hi) { unsigned r; asm volatile("v_cvt_pk_bf16_f32 %0, %1, %2" : "=v"(r) : "v"(lo), "v"(hi)); return r; }
;     __device__ __forceinline__ void operator()(const f32x4 (&acc)[2][2][4][2], const Unit& u, int wr, int wc, int fr, int fq) const {
;     ...
;         for (int ai = 0; ai < 2; ++ai)
; #pragma unroll
;             for (int m = 0; m < 4; ++m) { const int r = row0 + ai * HALF + m * 16; bf16_t* rowp = O + (size_t)r * ldc + col0; const float bb = bp[r];
; #pragma unroll
;                 for (int bj = 0; bj < 2; ++bj) { const f32x4 v0 = acc[ai][bj][m][0] * rs[bj][0] + bb, v1 = acc[ai][bj][m][1] * rs[bj][1] + bb;
;                     u32x4 w; w.x = cvt_pk_bf16(v0[0], v0[1]); w.y = cvt_pk_bf16(v0[2], v0[3]); w.z = cvt_pk_bf16(v1[0], v1[1]); w.w = cvt_pk_bf16(v1[2], v1[3]);
;                     *(u32x4*)(rowp + bj * HALF) = w; } }
	v_pk_fma_f32 v[126:127], v[126:127], v[152:153], v[174:175] op_sel_hi:[1,1,0]
	v_pk_fma_f32 v[124:125], v[124:125], v[150:151], v[174:175] op_sel_hi:[1,1,0]
	v_pk_fma_f32 v[176:177], v[122:123], v[132:133], v[174:175] op_sel_hi:[1,1,0]
	v_pk_fma_f32 v[122:123], v[120:121], v[154:155], v[174:175] op_sel_hi:[1,1,0]
	v_cvt_pk_bf16_f32 v120, v124, v125
	v_cvt_pk_bf16_f32 v121, v126, v127
	v_pk_fma_f32 v[116:117], v[116:117], v[158:159], v[174:175] op_sel_hi:[1,1,0]
	v_cvt_pk_bf16_f32 v122, v122, v123
	v_cvt_pk_bf16_f32 v123, v176, v177
	global_store_dwordx4 v[156:157], v[120:123], off sc1
	v_pk_fma_f32 v[118:119], v[118:119], v[160:161], v[174:175] op_sel_hi:[1,1,0]
	s_nop 0
	v_pk_fma_f32 v[120:121], v[114:115], v[130:131], v[174:175] op_sel_hi:[1,1,0]
	v_pk_fma_f32 v[114:115], v[112:113], v[128:129], v[174:175] op_sel_hi:[1,1,0]
	v_cvt_pk_bf16_f32 v112, v116, v117
	v_cvt_pk_bf16_f32 v113, v118, v119
	s_nop 0
	v_cvt_pk_bf16_f32 v114, v114, v115
	v_cvt_pk_bf16_f32 v115, v120, v121
	global_store_dwordx4 v[156:157], v[112:115], off offset:256 sc1
	s_nop 1
	v_or_b32_e32 v112, 16, v164
	v_ashrrev_i32_e32 v113, 31, v112
	v_lshl_add_u64 v[114:115], v[112:113], 2, s[8:9]
	global_load_dword v114, v[114:115], off
	v_lshlrev_b64 v[112:113], 16, v[112:113]
	v_lshl_add_u64 v[112:113], s[80:81], 0, v[112:113]
	v_lshl_add_u64 v[112:113], v[112:113], 0, v[178:179]
	s_waitcnt vmcnt(0)
	v_pk_fma_f32 v[110:111], v[110:111], v[152:153], v[114:115] op_sel_hi:[1,1,0]
	v_pk_fma_f32 v[108:109], v[108:109], v[150:151], v[114:115] op_sel_hi:[1,1,0]
	v_pk_fma_f32 v[116:117], v[106:107], v[132:133], v[114:115] op_sel_hi:[1,1,0]
	v_pk_fma_f32 v[106:107], v[104:105], v[154:155], v[114:115] op_sel_hi:[1,1,0]
	v_cvt_pk_bf16_f32 v104, v108, v109
	v_cvt_pk_bf16_f32 v105, v110, v111
	v_pk_fma_f32 v[100:101], v[100:101], v[158:159], v[114:115] op_sel_hi:[1,1,0]
	v_cvt_pk_bf16_f32 v106, v106, v107
	v_cvt_pk_bf16_f32 v107, v116, v117
	global_store_dwordx4 v[112:113], v[104:107], off sc1
	v_pk_fma_f32 v[102:103], v[102:103], v[160:161], v[114:115] op_sel_hi:[1,1,0]
	s_nop 0
	v_pk_fma_f32 v[104:105], v[98:99], v[130:131], v[114:115] op_sel_hi:[1,1,0]
	v_pk_fma_f32 v[98:99], v[96:97], v[128:129], v[114:115] op_sel_hi:[1,1,0]
	v_cvt_pk_bf16_f32 v96, v100, v101
	v_cvt_pk_bf16_f32 v97, v102, v103
	s_nop 0
	v_cvt_pk_bf16_f32 v98, v98, v99
	v_cvt_pk_bf16_f32 v99, v104, v105
	global_store_dwordx4 v[112:113], v[96:99], off offset:256 sc1
	s_nop 1
	v_or_b32_e32 v96, 32, v164
	v_ashrrev_i32_e32 v97, 31, v96
	v_lshl_add_u64 v[98:99], v[96:97], 2, s[8:9]
	global_load_dword v98, v[98:99], off
	v_lshlrev_b64 v[96:97], 16, v[96:97]
	v_lshl_add_u64 v[96:97], s[80:81], 0, v[96:97]
	v_lshl_add_u64 v[96:97], v[96:97], 0, v[178:179]
	s_waitcnt vmcnt(0)
	v_pk_fma_f32 v[94:95], v[94:95], v[152:153], v[98:99] op_sel_hi:[1,1,0]
	v_pk_fma_f32 v[92:93], v[92:93], v[150:151], v[98:99] op_sel_hi:[1,1,0]
	v_pk_fma_f32 v[100:101], v[90:91], v[132:133], v[98:99] op_sel_hi:[1,1,0]
	v_pk_fma_f32 v[90:91], v[88:89], v[154:155], v[98:99] op_sel_hi:[1,1,0]
	v_cvt_pk_bf16_f32 v88, v92, v93
	v_cvt_pk_bf16_f32 v89, v94, v95
	v_pk_fma_f32 v[84:85], v[84:85], v[158:159], v[98:99] op_sel_hi:[1,1,0]
	v_cvt_pk_bf16_f32 v90, v90, v91
	v_cvt_pk_bf16_f32 v91, v100, v101
	global_store_dwordx4 v[96:97], v[88:91], off sc1
	v_pk_fma_f32 v[86:87], v[86:87], v[160:161], v[98:99] op_sel_hi:[1,1,0]
	s_nop 0
	v_pk_fma_f32 v[88:89], v[82:83], v[130:131], v[98:99] op_sel_hi:[1,1,0]
	v_pk_fma_f32 v[82:83], v[80:81], v[128:129], v[98:99] op_sel_hi:[1,1,0]
	v_cvt_pk_bf16_f32 v80, v84, v85
	v_cvt_pk_bf16_f32 v81, v86, v87
	s_nop 0
	v_cvt_pk_bf16_f32 v82, v82, v83
	v_cvt_pk_bf16_f32 v83, v88, v89
	global_store_dwordx4 v[96:97], v[80:83], off offset:256 sc1
	s_nop 1
	v_or_b32_e32 v80, 48, v164
	v_ashrrev_i32_e32 v81, 31, v80
	v_lshl_add_u64 v[82:83], v[80:81], 2, s[8:9]
	global_load_dword v82, v[82:83], off
	v_lshlrev_b64 v[80:81], 16, v[80:81]
	v_lshl_add_u64 v[80:81], s[80:81], 0, v[80:81]
	v_lshl_add_u64 v[80:81], v[80:81], 0, v[178:179]
	s_waitcnt vmcnt(0)
	v_pk_fma_f32 v[78:79], v[78:79], v[152:153], v[82:83] op_sel_hi:[1,1,0]
	v_pk_fma_f32 v[76:77], v[76:77], v[150:151], v[82:83] op_sel_hi:[1,1,0]
	v_pk_fma_f32 v[84:85], v[74:75], v[132:133], v[82:83] op_sel_hi:[1,1,0]
	v_pk_fma_f32 v[74:75], v[72:73], v[154:155], v[82:83] op_sel_hi:[1,1,0]
	v_cvt_pk_bf16_f32 v72, v76, v77
	v_cvt_pk_bf16_f32 v73, v78, v79
	v_pk_fma_f32 v[70:71], v[70:71], v[160:161], v[82:83] op_sel_hi:[1,1,0]
	v_cvt_pk_bf16_f32 v74, v74, v75
	v_cvt_pk_bf16_f32 v75, v84, v85
	global_store_dwordx4 v[80:81], v[72:75], off sc1
	v_pk_fma_f32 v[68:69], v[68:69], v[158:159], v[82:83] op_sel_hi:[1,1,0]
	s_nop 0
	v_pk_fma_f32 v[72:73], v[66:67], v[130:131], v[82:83] op_sel_hi:[1,1,0]
	v_pk_fma_f32 v[66:67], v[64:65], v[128:129], v[82:83] op_sel_hi:[1,1,0]
	v_cvt_pk_bf16_f32 v64, v68, v69
	v_cvt_pk_bf16_f32 v65, v70, v71
	s_nop 0
	v_cvt_pk_bf16_f32 v66, v66, v67
	v_cvt_pk_bf16_f32 v67, v72, v73
	global_store_dwordx4 v[80:81], v[64:67], off offset:256 sc1
	global_load_dword v64, v[162:163], off offset:512
	s_waitcnt vmcnt(0)
; __device__ __forceinline__ unsigned cvt_pk_bf16(float lo, float hi) { unsigned r; asm volatile("v_cvt_pk_bf16_f32 %0, %1, %2" : "=v"(r) : "v"(lo), "v"(hi)); return r; }
;     __device__ __forceinline__ void operator()(const f32x4 (&acc)[2][2][4][2], const Unit& u, int wr, int wc, int fr, int fq) const {
;     ...
;         for (int ai = 0; ai < 2; ++ai)
; #pragma unroll
;             for (int m = 0; m < 4; ++m) { const int r = row0 + ai * HALF + m * 16; bf16_t* rowp = O + (size_t)r * ldc + col0; const float bb = bp[r];
; #pragma unroll
;                 for (int bj = 0; bj < 2; ++bj) { const f32x4 v0 = acc[ai][bj][m][0] * rs[bj][0] + bb, v1 = acc[ai][bj][m][1] * rs[bj][1] + bb;
;                     u32x4 w; w.x = cvt_pk_bf16(v0[0], v0[1]); w.y = cvt_pk_bf16(v0[2], v0[3]); w.z = cvt_pk_bf16(v1[0], v1[1]); w.w = cvt_pk_bf16(v1[2], v1[3]);
;                     *(u32x4*)(rowp + bj * HALF) = w; } }
	v_pk_fma_f32 v[60:61], v[60:61], v[150:151], v[64:65] op_sel_hi:[1,1,0]
	v_pk_fma_f32 v[68:69], v[58:59], v[132:133], v[64:65] op_sel_hi:[1,1,0]
	v_pk_fma_f32 v[58:59], v[56:57], v[154:155], v[64:65] op_sel_hi:[1,1,0]
	v_cvt_pk_bf16_f32 v56, v60, v61
	v_add_co_u32_e32 v60, vcc, s55, v156
	v_pk_fma_f32 v[62:63], v[62:63], v[152:153], v[64:65] op_sel_hi:[1,1,0]
	s_nop 0
	v_addc_co_u32_e32 v61, vcc, 0, v157, vcc
	v_cvt_pk_bf16_f32 v57, v62, v63
	v_lshl_add_u64 v[66:67], v[156:157], 0, s[20:21]
	v_cvt_pk_bf16_f32 v58, v58, v59
	v_cvt_pk_bf16_f32 v59, v68, v69
	global_store_dwordx4 v[60:61], v[56:59], off sc1
	v_pk_fma_f32 v[54:55], v[54:55], v[160:161], v[64:65] op_sel_hi:[1,1,0]
	v_pk_fma_f32 v[52:53], v[52:53], v[158:159], v[64:65] op_sel_hi:[1,1,0]
	v_pk_fma_f32 v[56:57], v[46:47], v[130:131], v[64:65] op_sel_hi:[1,1,0]
	v_pk_fma_f32 v[46:47], v[44:45], v[128:129], v[64:65] op_sel_hi:[1,1,0]
	v_cvt_pk_bf16_f32 v44, v52, v53
	v_cvt_pk_bf16_f32 v45, v54, v55
	s_nop 0
	v_cvt_pk_bf16_f32 v46, v46, v47
	v_cvt_pk_bf16_f32 v47, v56, v57
	global_store_dwordx4 v[66:67], v[44:47], off offset:256 sc1
	global_load_dword v44, v[162:163], off offset:576
	s_waitcnt vmcnt(0)
	v_pk_fma_f32 v[48:49], v[48:49], v[150:151], v[44:45] op_sel_hi:[1,1,0]
	v_pk_fma_f32 v[52:53], v[42:43], v[132:133], v[44:45] op_sel_hi:[1,1,0]
	v_pk_fma_f32 v[42:43], v[40:41], v[154:155], v[44:45] op_sel_hi:[1,1,0]
	v_cvt_pk_bf16_f32 v40, v48, v49
	v_add_co_u32_e32 v48, vcc, s56, v156
	v_pk_fma_f32 v[50:51], v[50:51], v[152:153], v[44:45] op_sel_hi:[1,1,0]
	s_nop 0
	v_addc_co_u32_e32 v49, vcc, 0, v157, vcc
	v_cvt_pk_bf16_f32 v41, v50, v51
	v_lshl_add_u64 v[46:47], v[156:157], 0, s[22:23]
	v_cvt_pk_bf16_f32 v42, v42, v43
	v_cvt_pk_bf16_f32 v43, v52, v53
	global_store_dwordx4 v[48:49], v[40:43], off sc1
	v_pk_fma_f32 v[38:39], v[38:39], v[160:161], v[44:45] op_sel_hi:[1,1,0]
	v_pk_fma_f32 v[36:37], v[36:37], v[158:159], v[44:45] op_sel_hi:[1,1,0]
	v_pk_fma_f32 v[40:41], v[30:31], v[130:131], v[44:45] op_sel_hi:[1,1,0]
	v_pk_fma_f32 v[30:31], v[28:29], v[128:129], v[44:45] op_sel_hi:[1,1,0]
	v_cvt_pk_bf16_f32 v28, v36, v37
	v_cvt_pk_bf16_f32 v29, v38, v39
	s_nop 0
	v_cvt_pk_bf16_f32 v30, v30, v31
	v_cvt_pk_bf16_f32 v31, v40, v41
	global_store_dwordx4 v[46:47], v[28:31], off offset:256 sc1
	global_load_dword v28, v[162:163], off offset:640
	s_waitcnt vmcnt(0)
	v_pk_fma_f32 v[32:33], v[32:33], v[150:151], v[28:29] op_sel_hi:[1,1,0]
	v_pk_fma_f32 v[36:37], v[26:27], v[132:133], v[28:29] op_sel_hi:[1,1,0]
	v_pk_fma_f32 v[26:27], v[24:25], v[154:155], v[28:29] op_sel_hi:[1,1,0]
	v_cvt_pk_bf16_f32 v24, v32, v33
	v_add_co_u32_e32 v32, vcc, s57, v156
	v_pk_fma_f32 v[34:35], v[34:35], v[152:153], v[28:29] op_sel_hi:[1,1,0]
	s_nop 0
	v_addc_co_u32_e32 v33, vcc, 0, v157, vcc
	v_cvt_pk_bf16_f32 v25, v34, v35
	v_lshl_add_u64 v[30:31], v[156:157], 0, s[24:25]
	v_cvt_pk_bf16_f32 v26, v26, v27
	v_cvt_pk_bf16_f32 v27, v36, v37
	global_store_dwordx4 v[32:33], v[24:27], off sc1
	v_pk_fma_f32 v[22:23], v[22:23], v[160:161], v[28:29] op_sel_hi:[1,1,0]
	v_pk_fma_f32 v[20:21], v[20:21], v[158:159], v[28:29] op_sel_hi:[1,1,0]
	v_pk_fma_f32 v[24:25], v[18:19], v[130:131], v[28:29] op_sel_hi:[1,1,0]
	v_pk_fma_f32 v[18:19], v[16:17], v[128:129], v[28:29] op_sel_hi:[1,1,0]
	v_cvt_pk_bf16_f32 v16, v20, v21
	v_cvt_pk_bf16_f32 v17, v22, v23
	v_add_co_u32_e32 v20, vcc, s58, v156
	v_cvt_pk_bf16_f32 v18, v18, v19
	v_cvt_pk_bf16_f32 v19, v24, v25
	global_store_dwordx4 v[30:31], v[16:19], off offset:256 sc1
	global_load_dword v16, v[162:163], off offset:704
	v_addc_co_u32_e32 v21, vcc, 0, v157, vcc
	v_lshl_add_u64 v[18:19], v[156:157], 0, s[26:27]
	s_andn2_b64 vcc, exec, s[0:1]
	s_mov_b64 s[0:1], -1
	s_waitcnt vmcnt(0)
	v_pk_fma_f32 v[14:15], v[14:15], v[152:153], v[16:17] op_sel_hi:[1,1,0]
	v_pk_fma_f32 v[12:13], v[12:13], v[150:151], v[16:17] op_sel_hi:[1,1,0]
	v_pk_fma_f32 v[10:11], v[10:11], v[132:133], v[16:17] op_sel_hi:[1,1,0]
	v_pk_fma_f32 v[8:9], v[8:9], v[154:155], v[16:17] op_sel_hi:[1,1,0]
	v_pk_fma_f32 v[6:7], v[6:7], v[160:161], v[16:17] op_sel_hi:[1,1,0]
	v_pk_fma_f32 v[4:5], v[4:5], v[158:159], v[16:17] op_sel_hi:[1,1,0]
	v_pk_fma_f32 v[22:23], v[2:3], v[130:131], v[16:17] op_sel_hi:[1,1,0]
	v_pk_fma_f32 v[16:17], v[0:1], v[128:129], v[16:17] op_sel_hi:[1,1,0]
	v_cvt_pk_bf16_f32 v0, v12, v13
	v_cvt_pk_bf16_f32 v1, v14, v15
	v_cvt_pk_bf16_f32 v2, v8, v9
	v_cvt_pk_bf16_f32 v3, v10, v11
	global_store_dwordx4 v[20:21], v[0:3], off sc1
	s_nop 1
	v_cvt_pk_bf16_f32 v0, v4, v5
	v_cvt_pk_bf16_f32 v1, v6, v7
	v_cvt_pk_bf16_f32 v2, v16, v17
	v_cvt_pk_bf16_f32 v3, v22, v23
	global_store_dwordx4 v[18:19], v[0:3], off offset:256 sc1
	s_cbranch_vccnz .LBB0_645
	s_andn2_b64 vcc, exec, s[14:15]
	s_cbranch_vccnz .LBB0_644
	s_barrier
	s_branch .LBB0_644
